# scan tiles: LDS waits merged (one s_waitcnt covers every read issued >=24 slots earlier): 91->24 and 112->63 s_waitcnt per 16-step tile
# speedup vs baseline: 1.0002x; 1.0002x over previous
; __device__ __forceinline__ void delta_scan_task(KP p, int l, bool samp, int b, int h, int cgp, float* sm) {
;     ...
;         for (int s0 = 0; s0 < nst; s0 += 4) {
; #pragma unroll
;             for (int s4 = 0; s4 < 4; ++s4) {
;                 const int s = s0 + s4;
;                 f32x2 k2[8], q2[8];
; #pragma unroll
;                 for (int hh = 0; hh < 4; ++hh) {
;                     const float4 a = *(const float4*)(bufp + s * 128 + ks * 16 + hh * 4);
;                     const float4 c = *(const float4*)(bufp + 2048 + s * 128 + ks * 16 + hh * 4);
;                     k2[2 * hh] = (f32x2){a.x, a.y}; k2[2 * hh + 1] = (f32x2){a.z, a.w};
;                     q2[2 * hh] = (f32x2){c.x, c.y}; q2[2 * hh + 1] = (f32x2){c.z, c.w};
;                 }
;                 const float vv = bufp[4096 + s * 32 + wid * 8 + cc];
;                 const float beta = bufp[4608 + s], alpha = bufp[4624 + s];
;                 f32x2 d0 = S[0] * k2[0], d1v = S[1] * k2[1], d2 = S[2] * k2[2], d3 = S[3] * k2[3];
;                 d0 = S[4] * k2[4] + d0; d1v = S[5] * k2[5] + d1v; d2 = S[6] * k2[6] + d2; d3 = S[7] * k2[7] + d3;
;                 d0 = (d0 + d1v) + (d2 + d3);
;                 const f32x2 al2 = (f32x2){alpha, alpha};
;                 f32x2 sa[8];
; #pragma unroll
;                 for (int j = 0; j < 8; ++j) sa[j] = S[j] * al2;
;                 const float dk = red8(d0.x + d0.y);
;                 const float vn = beta * (vv - alpha * dk);
;                 const f32x2 vn2 = (f32x2){vn, vn};
; #pragma unroll
;                 for (int j = 0; j < 8; ++j) S[j] = k2[j] * vn2 + sa[j];
;                 f32x2 o0 = S[0] * q2[0], o1 = S[1] * q2[1], o2 = S[2] * q2[2], o3 = S[3] * q2[3];
;                 o0 = S[4] * q2[4] + o0; o1 = S[5] * q2[5] + o1; o2 = S[6] * q2[6] + o2; o3 = S[7] * q2[7] + o3;
;                 o0 = (o0 + o1) + (o2 + o3);
;                 const float o = red8(o0.x + o0.y);
;                 oraw[(size_t)(row0 + tile * 16 + s) * 512 + h * 128 + e] = o;
;             }
.LBB0_147:
	v_add_u32_e32 v65, s11, v56
	v_add_u32_e32 v100, s11, v55
	s_add_i32 s2, s11, 0x4800
	v_mov_b32_e32 v234, s2
	s_mov_b32 s12, 0xfffff800
	s_mov_b32 s13, -1
	v_lshl_add_u64 v[28:29], v[26:27], 0, s[12:13]
	ds_read_b128 v[66:69], v65
	ds_read_b128 v[70:73], v65 offset:16
	ds_read_b128 v[74:77], v65 offset:32
	ds_read_b128 v[78:81], v65 offset:48
	ds_read_b128 v[14:17], v234 offset:64
	ds_read_b128 v[8:11], v234
	ds_read_b32 v58, v100
	ds_read_b32 v59, v100 offset:128
	ds_read_b32 v60, v100 offset:256
	ds_read_b32 v61, v100 offset:384
	ds_read_b128 v[82:85], v65 offset:512
	ds_read_b128 v[86:89], v65 offset:528
	ds_read_b128 v[90:93], v65 offset:544
	ds_read_b128 v[94:97], v65 offset:560
	s_waitcnt lgkmcnt(13)
	v_pk_mul_f32 v[62:63], v[30:31], v[66:67]
	v_pk_mul_f32 v[98:99], v[44:45], v[68:69]
	s_waitcnt lgkmcnt(12)
	v_pk_fma_f32 v[62:63], v[38:39], v[70:71], v[62:63]
	v_pk_fma_f32 v[98:99], v[36:37], v[72:73], v[98:99]
	s_waitcnt lgkmcnt(11)
	v_pk_fma_f32 v[62:63], v[34:35], v[74:75], v[62:63]
	v_pk_fma_f32 v[98:99], v[32:33], v[76:77], v[98:99]
	s_waitcnt lgkmcnt(10)
	v_pk_fma_f32 v[62:63], v[40:41], v[78:79], v[62:63]
	v_pk_fma_f32 v[98:99], v[42:43], v[80:81], v[98:99]
	s_nop 0
	v_pk_add_f32 v[62:63], v[62:63], v[98:99]
	ds_read_b128 v[236:239], v65 offset:8192
	ds_read_b128 v[240:243], v65 offset:8208
	ds_read_b128 v[244:247], v65 offset:8224
	ds_read_b128 v[248:251], v65 offset:8240
	v_add_f32_e32 v62, v62, v63
	s_waitcnt lgkmcnt(9)
	v_pk_mul_f32 v[30:31], v[30:31], v[14:15] op_sel_hi:[1,0]
	v_pk_mul_f32 v[44:45], v[44:45], v[14:15] op_sel_hi:[1,0]
	v_add_f32_dpp v62, v62, v62 quad_perm:[1,0,3,2] row_mask:0xf bank_mask:0xf bound_ctrl:1
	v_pk_mul_f32 v[38:39], v[38:39], v[14:15] op_sel_hi:[1,0]
	v_pk_mul_f32 v[36:37], v[36:37], v[14:15] op_sel_hi:[1,0]
	v_add_f32_dpp v62, v62, v62 quad_perm:[2,3,0,1] row_mask:0xf bank_mask:0xf bound_ctrl:1
	v_pk_mul_f32 v[34:35], v[34:35], v[14:15] op_sel_hi:[1,0]
	v_pk_mul_f32 v[32:33], v[32:33], v[14:15] op_sel_hi:[1,0]
	v_add_f32_dpp v62, v62, v62 row_half_mirror row_mask:0xf bank_mask:0xf bound_ctrl:1
	v_pk_mul_f32 v[40:41], v[40:41], v[14:15] op_sel_hi:[1,0]
	v_pk_mul_f32 v[42:43], v[42:43], v[14:15] op_sel_hi:[1,0]
	v_fma_f32 v63, -v14, v62, v58
	v_mul_f32_e32 v254, v8, v63
	v_pk_fma_f32 v[30:31], v[66:67], v[254:255], v[30:31] op_sel_hi:[1,0,1]
	v_pk_fma_f32 v[44:45], v[68:69], v[254:255], v[44:45] op_sel_hi:[1,0,1]
	v_pk_fma_f32 v[38:39], v[70:71], v[254:255], v[38:39] op_sel_hi:[1,0,1]
	v_pk_fma_f32 v[36:37], v[72:73], v[254:255], v[36:37] op_sel_hi:[1,0,1]
	v_pk_fma_f32 v[34:35], v[74:75], v[254:255], v[34:35] op_sel_hi:[1,0,1]
	v_pk_fma_f32 v[32:33], v[76:77], v[254:255], v[32:33] op_sel_hi:[1,0,1]
	v_pk_fma_f32 v[40:41], v[78:79], v[254:255], v[40:41] op_sel_hi:[1,0,1]
	v_pk_fma_f32 v[42:43], v[80:81], v[254:255], v[42:43] op_sel_hi:[1,0,1]
	ds_read_b128 v[66:69], v65 offset:1024
	ds_read_b128 v[70:73], v65 offset:1040
	ds_read_b128 v[74:77], v65 offset:1056
	ds_read_b128 v[78:81], v65 offset:1072
	s_waitcnt lgkmcnt(4)
	v_pk_mul_f32 v[62:63], v[30:31], v[82:83]
	v_pk_mul_f32 v[46:47], v[30:31], v[236:237]
	v_pk_mul_f32 v[98:99], v[44:45], v[84:85]
	v_pk_mul_f32 v[252:253], v[44:45], v[238:239]
	v_pk_fma_f32 v[62:63], v[38:39], v[86:87], v[62:63]
	v_pk_fma_f32 v[46:47], v[38:39], v[240:241], v[46:47]
	v_pk_fma_f32 v[98:99], v[36:37], v[88:89], v[98:99]
	v_pk_fma_f32 v[252:253], v[36:37], v[242:243], v[252:253]
	v_pk_fma_f32 v[62:63], v[34:35], v[90:91], v[62:63]
	v_pk_fma_f32 v[46:47], v[34:35], v[244:245], v[46:47]
	v_pk_fma_f32 v[98:99], v[32:33], v[92:93], v[98:99]
	v_pk_fma_f32 v[252:253], v[32:33], v[246:247], v[252:253]
	v_pk_fma_f32 v[62:63], v[40:41], v[94:95], v[62:63]
	v_pk_fma_f32 v[46:47], v[40:41], v[248:249], v[46:47]
	v_pk_fma_f32 v[98:99], v[42:43], v[96:97], v[98:99]
	v_pk_fma_f32 v[252:253], v[42:43], v[250:251], v[252:253]
	v_pk_add_f32 v[62:63], v[62:63], v[98:99]
	v_pk_add_f32 v[46:47], v[46:47], v[252:253]
	ds_read_b128 v[236:239], v65 offset:8704
	ds_read_b128 v[240:243], v65 offset:8720
	ds_read_b128 v[244:247], v65 offset:8736
	ds_read_b128 v[248:251], v65 offset:8752
	v_add_f32_e32 v62, v62, v63
	v_add_f32_e32 v46, v46, v47
	v_pk_mul_f32 v[30:31], v[30:31], v[14:15] op_sel:[0,1]
	v_pk_mul_f32 v[44:45], v[44:45], v[14:15] op_sel:[0,1]
	v_add_f32_dpp v62, v62, v62 quad_perm:[1,0,3,2] row_mask:0xf bank_mask:0xf bound_ctrl:1
	v_add_f32_dpp v46, v46, v46 quad_perm:[1,0,3,2] row_mask:0xf bank_mask:0xf bound_ctrl:1
	v_pk_mul_f32 v[38:39], v[38:39], v[14:15] op_sel:[0,1]
	v_pk_mul_f32 v[36:37], v[36:37], v[14:15] op_sel:[0,1]
	v_add_f32_dpp v62, v62, v62 quad_perm:[2,3,0,1] row_mask:0xf bank_mask:0xf bound_ctrl:1
	v_add_f32_dpp v46, v46, v46 quad_perm:[2,3,0,1] row_mask:0xf bank_mask:0xf bound_ctrl:1
	v_pk_mul_f32 v[34:35], v[34:35], v[14:15] op_sel:[0,1]
	v_pk_mul_f32 v[32:33], v[32:33], v[14:15] op_sel:[0,1]
	v_add_f32_dpp v62, v62, v62 row_half_mirror row_mask:0xf bank_mask:0xf bound_ctrl:1
	v_add_f32_dpp v46, v46, v46 row_half_mirror row_mask:0xf bank_mask:0xf bound_ctrl:1
	v_pk_mul_f32 v[40:41], v[40:41], v[14:15] op_sel:[0,1]
	v_pk_mul_f32 v[42:43], v[42:43], v[14:15] op_sel:[0,1]
	v_fma_f32 v63, -v15, v62, v59
	v_mul_f32_e32 v254, v9, v63
	global_store_dword v[28:29], v46, off offset:-4096
	v_pk_fma_f32 v[30:31], v[82:83], v[254:255], v[30:31] op_sel_hi:[1,0,1]
	v_pk_fma_f32 v[44:45], v[84:85], v[254:255], v[44:45] op_sel_hi:[1,0,1]
	v_pk_fma_f32 v[38:39], v[86:87], v[254:255], v[38:39] op_sel_hi:[1,0,1]
	v_pk_fma_f32 v[36:37], v[88:89], v[254:255], v[36:37] op_sel_hi:[1,0,1]
	v_pk_fma_f32 v[34:35], v[90:91], v[254:255], v[34:35] op_sel_hi:[1,0,1]
	v_pk_fma_f32 v[32:33], v[92:93], v[254:255], v[32:33] op_sel_hi:[1,0,1]
	v_pk_fma_f32 v[40:41], v[94:95], v[254:255], v[40:41] op_sel_hi:[1,0,1]
	v_pk_fma_f32 v[42:43], v[96:97], v[254:255], v[42:43] op_sel_hi:[1,0,1]
	ds_read_b128 v[82:85], v65 offset:1536
	ds_read_b128 v[86:89], v65 offset:1552
	ds_read_b128 v[90:93], v65 offset:1568
	ds_read_b128 v[94:97], v65 offset:1584
	s_waitcnt lgkmcnt(4)
; __device__ __forceinline__ void delta_scan_task(KP p, int l, bool samp, int b, int h, int cgp, float* sm) {
;     ...
;         for (int s0 = 0; s0 < nst; s0 += 4) {
; #pragma unroll
;             for (int s4 = 0; s4 < 4; ++s4) {
;                 const int s = s0 + s4;
;                 f32x2 k2[8], q2[8];
; #pragma unroll
;                 for (int hh = 0; hh < 4; ++hh) {
;                     const float4 a = *(const float4*)(bufp + s * 128 + ks * 16 + hh * 4);
;                     const float4 c = *(const float4*)(bufp + 2048 + s * 128 + ks * 16 + hh * 4);
;                     k2[2 * hh] = (f32x2){a.x, a.y}; k2[2 * hh + 1] = (f32x2){a.z, a.w};
;                     q2[2 * hh] = (f32x2){c.x, c.y}; q2[2 * hh + 1] = (f32x2){c.z, c.w};
;                 }
;                 const float vv = bufp[4096 + s * 32 + wid * 8 + cc];
;                 const float beta = bufp[4608 + s], alpha = bufp[4624 + s];
;                 f32x2 d0 = S[0] * k2[0], d1v = S[1] * k2[1], d2 = S[2] * k2[2], d3 = S[3] * k2[3];
;                 d0 = S[4] * k2[4] + d0; d1v = S[5] * k2[5] + d1v; d2 = S[6] * k2[6] + d2; d3 = S[7] * k2[7] + d3;
;                 d0 = (d0 + d1v) + (d2 + d3);
;                 const f32x2 al2 = (f32x2){alpha, alpha};
;                 f32x2 sa[8];
; #pragma unroll
;                 for (int j = 0; j < 8; ++j) sa[j] = S[j] * al2;
;                 const float dk = red8(d0.x + d0.y);
;                 const float vn = beta * (vv - alpha * dk);
;                 const f32x2 vn2 = (f32x2){vn, vn};
; #pragma unroll
;                 for (int j = 0; j < 8; ++j) S[j] = k2[j] * vn2 + sa[j];
;                 f32x2 o0 = S[0] * q2[0], o1 = S[1] * q2[1], o2 = S[2] * q2[2], o3 = S[3] * q2[3];
;                 o0 = S[4] * q2[4] + o0; o1 = S[5] * q2[5] + o1; o2 = S[6] * q2[6] + o2; o3 = S[7] * q2[7] + o3;
;                 o0 = (o0 + o1) + (o2 + o3);
;                 const float o = red8(o0.x + o0.y);
;                 oraw[(size_t)(row0 + tile * 16 + s) * 512 + h * 128 + e] = o;
;             }
	v_pk_mul_f32 v[62:63], v[30:31], v[66:67]
	v_pk_mul_f32 v[46:47], v[30:31], v[236:237]
	v_pk_mul_f32 v[98:99], v[44:45], v[68:69]
	v_pk_mul_f32 v[252:253], v[44:45], v[238:239]
	v_pk_fma_f32 v[62:63], v[38:39], v[70:71], v[62:63]
	v_pk_fma_f32 v[46:47], v[38:39], v[240:241], v[46:47]
	v_pk_fma_f32 v[98:99], v[36:37], v[72:73], v[98:99]
	v_pk_fma_f32 v[252:253], v[36:37], v[242:243], v[252:253]
	v_pk_fma_f32 v[62:63], v[34:35], v[74:75], v[62:63]
	v_pk_fma_f32 v[46:47], v[34:35], v[244:245], v[46:47]
	v_pk_fma_f32 v[98:99], v[32:33], v[76:77], v[98:99]
	v_pk_fma_f32 v[252:253], v[32:33], v[246:247], v[252:253]
	v_pk_fma_f32 v[62:63], v[40:41], v[78:79], v[62:63]
	v_pk_fma_f32 v[46:47], v[40:41], v[248:249], v[46:47]
	v_pk_fma_f32 v[98:99], v[42:43], v[80:81], v[98:99]
	v_pk_fma_f32 v[252:253], v[42:43], v[250:251], v[252:253]
	v_pk_add_f32 v[62:63], v[62:63], v[98:99]
	v_pk_add_f32 v[46:47], v[46:47], v[252:253]
	ds_read_b128 v[236:239], v65 offset:9216
	ds_read_b128 v[240:243], v65 offset:9232
	ds_read_b128 v[244:247], v65 offset:9248
	ds_read_b128 v[248:251], v65 offset:9264
	v_add_f32_e32 v62, v62, v63
	v_add_f32_e32 v46, v46, v47
	v_pk_mul_f32 v[30:31], v[30:31], v[16:17] op_sel_hi:[1,0]
	v_pk_mul_f32 v[44:45], v[44:45], v[16:17] op_sel_hi:[1,0]
	v_add_f32_dpp v62, v62, v62 quad_perm:[1,0,3,2] row_mask:0xf bank_mask:0xf bound_ctrl:1
	v_add_f32_dpp v46, v46, v46 quad_perm:[1,0,3,2] row_mask:0xf bank_mask:0xf bound_ctrl:1
	v_pk_mul_f32 v[38:39], v[38:39], v[16:17] op_sel_hi:[1,0]
	v_pk_mul_f32 v[36:37], v[36:37], v[16:17] op_sel_hi:[1,0]
	v_add_f32_dpp v62, v62, v62 quad_perm:[2,3,0,1] row_mask:0xf bank_mask:0xf bound_ctrl:1
	v_add_f32_dpp v46, v46, v46 quad_perm:[2,3,0,1] row_mask:0xf bank_mask:0xf bound_ctrl:1
	v_pk_mul_f32 v[34:35], v[34:35], v[16:17] op_sel_hi:[1,0]
	v_pk_mul_f32 v[32:33], v[32:33], v[16:17] op_sel_hi:[1,0]
	v_add_f32_dpp v62, v62, v62 row_half_mirror row_mask:0xf bank_mask:0xf bound_ctrl:1
	v_add_f32_dpp v46, v46, v46 row_half_mirror row_mask:0xf bank_mask:0xf bound_ctrl:1
	v_pk_mul_f32 v[40:41], v[40:41], v[16:17] op_sel_hi:[1,0]
	v_pk_mul_f32 v[42:43], v[42:43], v[16:17] op_sel_hi:[1,0]
	v_fma_f32 v63, -v16, v62, v60
	v_mul_f32_e32 v254, v10, v63
	global_store_dword v[28:29], v46, off offset:-2048
	v_pk_fma_f32 v[30:31], v[66:67], v[254:255], v[30:31] op_sel_hi:[1,0,1]
	v_pk_fma_f32 v[44:45], v[68:69], v[254:255], v[44:45] op_sel_hi:[1,0,1]
	v_pk_fma_f32 v[38:39], v[70:71], v[254:255], v[38:39] op_sel_hi:[1,0,1]
	v_pk_fma_f32 v[36:37], v[72:73], v[254:255], v[36:37] op_sel_hi:[1,0,1]
	v_pk_fma_f32 v[34:35], v[74:75], v[254:255], v[34:35] op_sel_hi:[1,0,1]
	v_pk_fma_f32 v[32:33], v[76:77], v[254:255], v[32:33] op_sel_hi:[1,0,1]
	v_pk_fma_f32 v[40:41], v[78:79], v[254:255], v[40:41] op_sel_hi:[1,0,1]
	v_pk_fma_f32 v[42:43], v[80:81], v[254:255], v[42:43] op_sel_hi:[1,0,1]
	ds_read_b128 v[66:69], v65 offset:2048
	ds_read_b128 v[70:73], v65 offset:2064
	ds_read_b128 v[74:77], v65 offset:2080
	ds_read_b128 v[78:81], v65 offset:2096
	s_waitcnt lgkmcnt(4)
	v_pk_mul_f32 v[62:63], v[30:31], v[82:83]
	v_pk_mul_f32 v[46:47], v[30:31], v[236:237]
	v_pk_mul_f32 v[98:99], v[44:45], v[84:85]
	v_pk_mul_f32 v[252:253], v[44:45], v[238:239]
	v_pk_fma_f32 v[62:63], v[38:39], v[86:87], v[62:63]
	v_pk_fma_f32 v[46:47], v[38:39], v[240:241], v[46:47]
	v_pk_fma_f32 v[98:99], v[36:37], v[88:89], v[98:99]
	v_pk_fma_f32 v[252:253], v[36:37], v[242:243], v[252:253]
	v_pk_fma_f32 v[62:63], v[34:35], v[90:91], v[62:63]
	v_pk_fma_f32 v[46:47], v[34:35], v[244:245], v[46:47]
	v_pk_fma_f32 v[98:99], v[32:33], v[92:93], v[98:99]
	v_pk_fma_f32 v[252:253], v[32:33], v[246:247], v[252:253]
	v_pk_fma_f32 v[62:63], v[40:41], v[94:95], v[62:63]
	v_pk_fma_f32 v[46:47], v[40:41], v[248:249], v[46:47]
	v_pk_fma_f32 v[98:99], v[42:43], v[96:97], v[98:99]
	v_pk_fma_f32 v[252:253], v[42:43], v[250:251], v[252:253]
	v_pk_add_f32 v[62:63], v[62:63], v[98:99]
	v_pk_add_f32 v[46:47], v[46:47], v[252:253]
	ds_read_b128 v[236:239], v65 offset:9728
	ds_read_b128 v[240:243], v65 offset:9744
	ds_read_b128 v[244:247], v65 offset:9760
	ds_read_b128 v[248:251], v65 offset:9776
	v_add_f32_e32 v62, v62, v63
	v_add_f32_e32 v46, v46, v47
	v_pk_mul_f32 v[30:31], v[30:31], v[16:17] op_sel:[0,1]
	v_pk_mul_f32 v[44:45], v[44:45], v[16:17] op_sel:[0,1]
	v_add_f32_dpp v62, v62, v62 quad_perm:[1,0,3,2] row_mask:0xf bank_mask:0xf bound_ctrl:1
	v_add_f32_dpp v46, v46, v46 quad_perm:[1,0,3,2] row_mask:0xf bank_mask:0xf bound_ctrl:1
	v_pk_mul_f32 v[38:39], v[38:39], v[16:17] op_sel:[0,1]
	v_pk_mul_f32 v[36:37], v[36:37], v[16:17] op_sel:[0,1]
	v_add_f32_dpp v62, v62, v62 quad_perm:[2,3,0,1] row_mask:0xf bank_mask:0xf bound_ctrl:1
	v_add_f32_dpp v46, v46, v46 quad_perm:[2,3,0,1] row_mask:0xf bank_mask:0xf bound_ctrl:1
	v_pk_mul_f32 v[34:35], v[34:35], v[16:17] op_sel:[0,1]
	v_pk_mul_f32 v[32:33], v[32:33], v[16:17] op_sel:[0,1]
	v_add_f32_dpp v62, v62, v62 row_half_mirror row_mask:0xf bank_mask:0xf bound_ctrl:1
	v_add_f32_dpp v46, v46, v46 row_half_mirror row_mask:0xf bank_mask:0xf bound_ctrl:1
	v_pk_mul_f32 v[40:41], v[40:41], v[16:17] op_sel:[0,1]
	v_pk_mul_f32 v[42:43], v[42:43], v[16:17] op_sel:[0,1]
	v_fma_f32 v63, -v17, v62, v61
	v_mul_f32_e32 v254, v11, v63
	global_store_dword v[28:29], v46, off
	v_pk_fma_f32 v[30:31], v[82:83], v[254:255], v[30:31] op_sel_hi:[1,0,1]
	v_pk_fma_f32 v[44:45], v[84:85], v[254:255], v[44:45] op_sel_hi:[1,0,1]
	v_pk_fma_f32 v[38:39], v[86:87], v[254:255], v[38:39] op_sel_hi:[1,0,1]
	v_pk_fma_f32 v[36:37], v[88:89], v[254:255], v[36:37] op_sel_hi:[1,0,1]
	v_pk_fma_f32 v[34:35], v[90:91], v[254:255], v[34:35] op_sel_hi:[1,0,1]
	v_pk_fma_f32 v[32:33], v[92:93], v[254:255], v[32:33] op_sel_hi:[1,0,1]
	v_pk_fma_f32 v[40:41], v[94:95], v[254:255], v[40:41] op_sel_hi:[1,0,1]
	v_pk_fma_f32 v[42:43], v[96:97], v[254:255], v[42:43] op_sel_hi:[1,0,1]
	ds_read_b128 v[14:17], v234 offset:80
	ds_read_b128 v[8:11], v234 offset:16
	ds_read_b32 v58, v100 offset:512
	ds_read_b32 v59, v100 offset:640
	ds_read_b32 v60, v100 offset:768
	ds_read_b32 v61, v100 offset:896
	ds_read_b128 v[82:85], v65 offset:2560
	ds_read_b128 v[86:89], v65 offset:2576
	ds_read_b128 v[90:93], v65 offset:2592
	ds_read_b128 v[94:97], v65 offset:2608
	s_waitcnt lgkmcnt(10)
; __device__ __forceinline__ void delta_scan_task(KP p, int l, bool samp, int b, int h, int cgp, float* sm) {
;     ...
;         for (int s0 = 0; s0 < nst; s0 += 4) {
; #pragma unroll
;             for (int s4 = 0; s4 < 4; ++s4) {
;                 const int s = s0 + s4;
;                 f32x2 k2[8], q2[8];
; #pragma unroll
;                 for (int hh = 0; hh < 4; ++hh) {
;                     const float4 a = *(const float4*)(bufp + s * 128 + ks * 16 + hh * 4);
;                     const float4 c = *(const float4*)(bufp + 2048 + s * 128 + ks * 16 + hh * 4);
;                     k2[2 * hh] = (f32x2){a.x, a.y}; k2[2 * hh + 1] = (f32x2){a.z, a.w};
;                     q2[2 * hh] = (f32x2){c.x, c.y}; q2[2 * hh + 1] = (f32x2){c.z, c.w};
;                 }
;                 const float vv = bufp[4096 + s * 32 + wid * 8 + cc];
;                 const float beta = bufp[4608 + s], alpha = bufp[4624 + s];
;                 f32x2 d0 = S[0] * k2[0], d1v = S[1] * k2[1], d2 = S[2] * k2[2], d3 = S[3] * k2[3];
;                 d0 = S[4] * k2[4] + d0; d1v = S[5] * k2[5] + d1v; d2 = S[6] * k2[6] + d2; d3 = S[7] * k2[7] + d3;
;                 d0 = (d0 + d1v) + (d2 + d3);
;                 const f32x2 al2 = (f32x2){alpha, alpha};
;                 f32x2 sa[8];
; #pragma unroll
;                 for (int j = 0; j < 8; ++j) sa[j] = S[j] * al2;
;                 const float dk = red8(d0.x + d0.y);
;                 const float vn = beta * (vv - alpha * dk);
;                 const f32x2 vn2 = (f32x2){vn, vn};
; #pragma unroll
;                 for (int j = 0; j < 8; ++j) S[j] = k2[j] * vn2 + sa[j];
;                 f32x2 o0 = S[0] * q2[0], o1 = S[1] * q2[1], o2 = S[2] * q2[2], o3 = S[3] * q2[3];
;                 o0 = S[4] * q2[4] + o0; o1 = S[5] * q2[5] + o1; o2 = S[6] * q2[6] + o2; o3 = S[7] * q2[7] + o3;
;                 o0 = (o0 + o1) + (o2 + o3);
;                 const float o = red8(o0.x + o0.y);
;                 oraw[(size_t)(row0 + tile * 16 + s) * 512 + h * 128 + e] = o;
;             }
	v_pk_mul_f32 v[62:63], v[30:31], v[66:67]
	v_pk_mul_f32 v[46:47], v[30:31], v[236:237]
	v_pk_mul_f32 v[98:99], v[44:45], v[68:69]
	v_pk_mul_f32 v[252:253], v[44:45], v[238:239]
	v_pk_fma_f32 v[62:63], v[38:39], v[70:71], v[62:63]
	v_pk_fma_f32 v[46:47], v[38:39], v[240:241], v[46:47]
	v_pk_fma_f32 v[98:99], v[36:37], v[72:73], v[98:99]
	v_pk_fma_f32 v[252:253], v[36:37], v[242:243], v[252:253]
	v_pk_fma_f32 v[62:63], v[34:35], v[74:75], v[62:63]
	v_pk_fma_f32 v[46:47], v[34:35], v[244:245], v[46:47]
	v_pk_fma_f32 v[98:99], v[32:33], v[76:77], v[98:99]
	v_pk_fma_f32 v[252:253], v[32:33], v[246:247], v[252:253]
	v_pk_fma_f32 v[62:63], v[40:41], v[78:79], v[62:63]
	v_pk_fma_f32 v[46:47], v[40:41], v[248:249], v[46:47]
	v_pk_fma_f32 v[98:99], v[42:43], v[80:81], v[98:99]
	v_pk_fma_f32 v[252:253], v[42:43], v[250:251], v[252:253]
	v_pk_add_f32 v[62:63], v[62:63], v[98:99]
	v_pk_add_f32 v[46:47], v[46:47], v[252:253]
	ds_read_b128 v[236:239], v65 offset:10240
	ds_read_b128 v[240:243], v65 offset:10256
	ds_read_b128 v[244:247], v65 offset:10272
	ds_read_b128 v[248:251], v65 offset:10288
	v_add_f32_e32 v62, v62, v63
	v_add_f32_e32 v46, v46, v47
	s_waitcnt lgkmcnt(4)
	v_pk_mul_f32 v[30:31], v[30:31], v[14:15] op_sel_hi:[1,0]
	v_pk_mul_f32 v[44:45], v[44:45], v[14:15] op_sel_hi:[1,0]
	v_add_f32_dpp v62, v62, v62 quad_perm:[1,0,3,2] row_mask:0xf bank_mask:0xf bound_ctrl:1
	v_add_f32_dpp v46, v46, v46 quad_perm:[1,0,3,2] row_mask:0xf bank_mask:0xf bound_ctrl:1
	v_pk_mul_f32 v[38:39], v[38:39], v[14:15] op_sel_hi:[1,0]
	v_pk_mul_f32 v[36:37], v[36:37], v[14:15] op_sel_hi:[1,0]
	v_add_f32_dpp v62, v62, v62 quad_perm:[2,3,0,1] row_mask:0xf bank_mask:0xf bound_ctrl:1
	v_add_f32_dpp v46, v46, v46 quad_perm:[2,3,0,1] row_mask:0xf bank_mask:0xf bound_ctrl:1
	v_pk_mul_f32 v[34:35], v[34:35], v[14:15] op_sel_hi:[1,0]
	v_pk_mul_f32 v[32:33], v[32:33], v[14:15] op_sel_hi:[1,0]
	v_add_f32_dpp v62, v62, v62 row_half_mirror row_mask:0xf bank_mask:0xf bound_ctrl:1
	v_add_f32_dpp v46, v46, v46 row_half_mirror row_mask:0xf bank_mask:0xf bound_ctrl:1
	v_pk_mul_f32 v[40:41], v[40:41], v[14:15] op_sel_hi:[1,0]
	v_pk_mul_f32 v[42:43], v[42:43], v[14:15] op_sel_hi:[1,0]
	v_fma_f32 v63, -v14, v62, v58
	v_mul_f32_e32 v254, v8, v63
	global_store_dword v[28:29], v46, off offset:2048
	v_lshl_add_u64 v[28:29], v[28:29], 0, s[20:21]
	v_pk_fma_f32 v[30:31], v[66:67], v[254:255], v[30:31] op_sel_hi:[1,0,1]
	v_pk_fma_f32 v[44:45], v[68:69], v[254:255], v[44:45] op_sel_hi:[1,0,1]
	v_pk_fma_f32 v[38:39], v[70:71], v[254:255], v[38:39] op_sel_hi:[1,0,1]
	v_pk_fma_f32 v[36:37], v[72:73], v[254:255], v[36:37] op_sel_hi:[1,0,1]
	v_pk_fma_f32 v[34:35], v[74:75], v[254:255], v[34:35] op_sel_hi:[1,0,1]
	v_pk_fma_f32 v[32:33], v[76:77], v[254:255], v[32:33] op_sel_hi:[1,0,1]
	v_pk_fma_f32 v[40:41], v[78:79], v[254:255], v[40:41] op_sel_hi:[1,0,1]
	v_pk_fma_f32 v[42:43], v[80:81], v[254:255], v[42:43] op_sel_hi:[1,0,1]
	ds_read_b128 v[66:69], v65 offset:3072
	ds_read_b128 v[70:73], v65 offset:3088
	ds_read_b128 v[74:77], v65 offset:3104
	ds_read_b128 v[78:81], v65 offset:3120
	v_pk_mul_f32 v[62:63], v[30:31], v[82:83]
	s_waitcnt lgkmcnt(4)
	v_pk_mul_f32 v[46:47], v[30:31], v[236:237]
	v_pk_mul_f32 v[98:99], v[44:45], v[84:85]
	v_pk_mul_f32 v[252:253], v[44:45], v[238:239]
	v_pk_fma_f32 v[62:63], v[38:39], v[86:87], v[62:63]
	v_pk_fma_f32 v[46:47], v[38:39], v[240:241], v[46:47]
	v_pk_fma_f32 v[98:99], v[36:37], v[88:89], v[98:99]
	v_pk_fma_f32 v[252:253], v[36:37], v[242:243], v[252:253]
	v_pk_fma_f32 v[62:63], v[34:35], v[90:91], v[62:63]
	v_pk_fma_f32 v[46:47], v[34:35], v[244:245], v[46:47]
	v_pk_fma_f32 v[98:99], v[32:33], v[92:93], v[98:99]
	v_pk_fma_f32 v[252:253], v[32:33], v[246:247], v[252:253]
	v_pk_fma_f32 v[62:63], v[40:41], v[94:95], v[62:63]
	v_pk_fma_f32 v[46:47], v[40:41], v[248:249], v[46:47]
	v_pk_fma_f32 v[98:99], v[42:43], v[96:97], v[98:99]
	v_pk_fma_f32 v[252:253], v[42:43], v[250:251], v[252:253]
	v_pk_add_f32 v[62:63], v[62:63], v[98:99]
	v_pk_add_f32 v[46:47], v[46:47], v[252:253]
	ds_read_b128 v[236:239], v65 offset:10752
	ds_read_b128 v[240:243], v65 offset:10768
	ds_read_b128 v[244:247], v65 offset:10784
	ds_read_b128 v[248:251], v65 offset:10800
	v_add_f32_e32 v62, v62, v63
	v_add_f32_e32 v46, v46, v47
	v_pk_mul_f32 v[30:31], v[30:31], v[14:15] op_sel:[0,1]
	v_pk_mul_f32 v[44:45], v[44:45], v[14:15] op_sel:[0,1]
	v_add_f32_dpp v62, v62, v62 quad_perm:[1,0,3,2] row_mask:0xf bank_mask:0xf bound_ctrl:1
	v_add_f32_dpp v46, v46, v46 quad_perm:[1,0,3,2] row_mask:0xf bank_mask:0xf bound_ctrl:1
	v_pk_mul_f32 v[38:39], v[38:39], v[14:15] op_sel:[0,1]
	v_pk_mul_f32 v[36:37], v[36:37], v[14:15] op_sel:[0,1]
	v_add_f32_dpp v62, v62, v62 quad_perm:[2,3,0,1] row_mask:0xf bank_mask:0xf bound_ctrl:1
	v_add_f32_dpp v46, v46, v46 quad_perm:[2,3,0,1] row_mask:0xf bank_mask:0xf bound_ctrl:1
	v_pk_mul_f32 v[34:35], v[34:35], v[14:15] op_sel:[0,1]
	v_pk_mul_f32 v[32:33], v[32:33], v[14:15] op_sel:[0,1]
	v_add_f32_dpp v62, v62, v62 row_half_mirror row_mask:0xf bank_mask:0xf bound_ctrl:1
	v_add_f32_dpp v46, v46, v46 row_half_mirror row_mask:0xf bank_mask:0xf bound_ctrl:1
	v_pk_mul_f32 v[40:41], v[40:41], v[14:15] op_sel:[0,1]
	v_pk_mul_f32 v[42:43], v[42:43], v[14:15] op_sel:[0,1]
	v_fma_f32 v63, -v15, v62, v59
	v_mul_f32_e32 v254, v9, v63
	global_store_dword v[28:29], v46, off offset:-4096
	v_pk_fma_f32 v[30:31], v[82:83], v[254:255], v[30:31] op_sel_hi:[1,0,1]
	v_pk_fma_f32 v[44:45], v[84:85], v[254:255], v[44:45] op_sel_hi:[1,0,1]
	v_pk_fma_f32 v[38:39], v[86:87], v[254:255], v[38:39] op_sel_hi:[1,0,1]
	v_pk_fma_f32 v[36:37], v[88:89], v[254:255], v[36:37] op_sel_hi:[1,0,1]
	v_pk_fma_f32 v[34:35], v[90:91], v[254:255], v[34:35] op_sel_hi:[1,0,1]
	v_pk_fma_f32 v[32:33], v[92:93], v[254:255], v[32:33] op_sel_hi:[1,0,1]
	v_pk_fma_f32 v[40:41], v[94:95], v[254:255], v[40:41] op_sel_hi:[1,0,1]
	v_pk_fma_f32 v[42:43], v[96:97], v[254:255], v[42:43] op_sel_hi:[1,0,1]
	ds_read_b128 v[82:85], v65 offset:3584
	ds_read_b128 v[86:89], v65 offset:3600
	ds_read_b128 v[90:93], v65 offset:3616
	ds_read_b128 v[94:97], v65 offset:3632
	s_waitcnt lgkmcnt(4)
; __device__ __forceinline__ void delta_scan_task(KP p, int l, bool samp, int b, int h, int cgp, float* sm) {
;     ...
;         for (int s0 = 0; s0 < nst; s0 += 4) {
; #pragma unroll
;             for (int s4 = 0; s4 < 4; ++s4) {
;                 const int s = s0 + s4;
;                 f32x2 k2[8], q2[8];
; #pragma unroll
;                 for (int hh = 0; hh < 4; ++hh) {
;                     const float4 a = *(const float4*)(bufp + s * 128 + ks * 16 + hh * 4);
;                     const float4 c = *(const float4*)(bufp + 2048 + s * 128 + ks * 16 + hh * 4);
;                     k2[2 * hh] = (f32x2){a.x, a.y}; k2[2 * hh + 1] = (f32x2){a.z, a.w};
;                     q2[2 * hh] = (f32x2){c.x, c.y}; q2[2 * hh + 1] = (f32x2){c.z, c.w};
;                 }
;                 const float vv = bufp[4096 + s * 32 + wid * 8 + cc];
;                 const float beta = bufp[4608 + s], alpha = bufp[4624 + s];
;                 f32x2 d0 = S[0] * k2[0], d1v = S[1] * k2[1], d2 = S[2] * k2[2], d3 = S[3] * k2[3];
;                 d0 = S[4] * k2[4] + d0; d1v = S[5] * k2[5] + d1v; d2 = S[6] * k2[6] + d2; d3 = S[7] * k2[7] + d3;
;                 d0 = (d0 + d1v) + (d2 + d3);
;                 const f32x2 al2 = (f32x2){alpha, alpha};
;                 f32x2 sa[8];
; #pragma unroll
;                 for (int j = 0; j < 8; ++j) sa[j] = S[j] * al2;
;                 const float dk = red8(d0.x + d0.y);
;                 const float vn = beta * (vv - alpha * dk);
;                 const f32x2 vn2 = (f32x2){vn, vn};
; #pragma unroll
;                 for (int j = 0; j < 8; ++j) S[j] = k2[j] * vn2 + sa[j];
;                 f32x2 o0 = S[0] * q2[0], o1 = S[1] * q2[1], o2 = S[2] * q2[2], o3 = S[3] * q2[3];
;                 o0 = S[4] * q2[4] + o0; o1 = S[5] * q2[5] + o1; o2 = S[6] * q2[6] + o2; o3 = S[7] * q2[7] + o3;
;                 o0 = (o0 + o1) + (o2 + o3);
;                 const float o = red8(o0.x + o0.y);
;                 oraw[(size_t)(row0 + tile * 16 + s) * 512 + h * 128 + e] = o;
;             }
	v_pk_mul_f32 v[62:63], v[30:31], v[66:67]
	v_pk_mul_f32 v[46:47], v[30:31], v[236:237]
	v_pk_mul_f32 v[98:99], v[44:45], v[68:69]
	v_pk_mul_f32 v[252:253], v[44:45], v[238:239]
	v_pk_fma_f32 v[62:63], v[38:39], v[70:71], v[62:63]
	v_pk_fma_f32 v[46:47], v[38:39], v[240:241], v[46:47]
	v_pk_fma_f32 v[98:99], v[36:37], v[72:73], v[98:99]
	v_pk_fma_f32 v[252:253], v[36:37], v[242:243], v[252:253]
	v_pk_fma_f32 v[62:63], v[34:35], v[74:75], v[62:63]
	v_pk_fma_f32 v[46:47], v[34:35], v[244:245], v[46:47]
	v_pk_fma_f32 v[98:99], v[32:33], v[76:77], v[98:99]
	v_pk_fma_f32 v[252:253], v[32:33], v[246:247], v[252:253]
	v_pk_fma_f32 v[62:63], v[40:41], v[78:79], v[62:63]
	v_pk_fma_f32 v[46:47], v[40:41], v[248:249], v[46:47]
	v_pk_fma_f32 v[98:99], v[42:43], v[80:81], v[98:99]
	v_pk_fma_f32 v[252:253], v[42:43], v[250:251], v[252:253]
	v_pk_add_f32 v[62:63], v[62:63], v[98:99]
	v_pk_add_f32 v[46:47], v[46:47], v[252:253]
	ds_read_b128 v[236:239], v65 offset:11264
	ds_read_b128 v[240:243], v65 offset:11280
	ds_read_b128 v[244:247], v65 offset:11296
	ds_read_b128 v[248:251], v65 offset:11312
	v_add_f32_e32 v62, v62, v63
	v_add_f32_e32 v46, v46, v47
	v_pk_mul_f32 v[30:31], v[30:31], v[16:17] op_sel_hi:[1,0]
	v_pk_mul_f32 v[44:45], v[44:45], v[16:17] op_sel_hi:[1,0]
	v_add_f32_dpp v62, v62, v62 quad_perm:[1,0,3,2] row_mask:0xf bank_mask:0xf bound_ctrl:1
	v_add_f32_dpp v46, v46, v46 quad_perm:[1,0,3,2] row_mask:0xf bank_mask:0xf bound_ctrl:1
	v_pk_mul_f32 v[38:39], v[38:39], v[16:17] op_sel_hi:[1,0]
	v_pk_mul_f32 v[36:37], v[36:37], v[16:17] op_sel_hi:[1,0]
	v_add_f32_dpp v62, v62, v62 quad_perm:[2,3,0,1] row_mask:0xf bank_mask:0xf bound_ctrl:1
	v_add_f32_dpp v46, v46, v46 quad_perm:[2,3,0,1] row_mask:0xf bank_mask:0xf bound_ctrl:1
	v_pk_mul_f32 v[34:35], v[34:35], v[16:17] op_sel_hi:[1,0]
	v_pk_mul_f32 v[32:33], v[32:33], v[16:17] op_sel_hi:[1,0]
	v_add_f32_dpp v62, v62, v62 row_half_mirror row_mask:0xf bank_mask:0xf bound_ctrl:1
	v_add_f32_dpp v46, v46, v46 row_half_mirror row_mask:0xf bank_mask:0xf bound_ctrl:1
	v_pk_mul_f32 v[40:41], v[40:41], v[16:17] op_sel_hi:[1,0]
	v_pk_mul_f32 v[42:43], v[42:43], v[16:17] op_sel_hi:[1,0]
	v_fma_f32 v63, -v16, v62, v60
	v_mul_f32_e32 v254, v10, v63
	global_store_dword v[28:29], v46, off offset:-2048
	v_pk_fma_f32 v[30:31], v[66:67], v[254:255], v[30:31] op_sel_hi:[1,0,1]
	v_pk_fma_f32 v[44:45], v[68:69], v[254:255], v[44:45] op_sel_hi:[1,0,1]
	v_pk_fma_f32 v[38:39], v[70:71], v[254:255], v[38:39] op_sel_hi:[1,0,1]
	v_pk_fma_f32 v[36:37], v[72:73], v[254:255], v[36:37] op_sel_hi:[1,0,1]
	v_pk_fma_f32 v[34:35], v[74:75], v[254:255], v[34:35] op_sel_hi:[1,0,1]
	v_pk_fma_f32 v[32:33], v[76:77], v[254:255], v[32:33] op_sel_hi:[1,0,1]
	v_pk_fma_f32 v[40:41], v[78:79], v[254:255], v[40:41] op_sel_hi:[1,0,1]
	v_pk_fma_f32 v[42:43], v[80:81], v[254:255], v[42:43] op_sel_hi:[1,0,1]
	ds_read_b128 v[66:69], v65 offset:4096
	ds_read_b128 v[70:73], v65 offset:4112
	ds_read_b128 v[74:77], v65 offset:4128
	ds_read_b128 v[78:81], v65 offset:4144
	s_waitcnt lgkmcnt(4)
	v_pk_mul_f32 v[62:63], v[30:31], v[82:83]
	v_pk_mul_f32 v[46:47], v[30:31], v[236:237]
	v_pk_mul_f32 v[98:99], v[44:45], v[84:85]
	v_pk_mul_f32 v[252:253], v[44:45], v[238:239]
	v_pk_fma_f32 v[62:63], v[38:39], v[86:87], v[62:63]
	v_pk_fma_f32 v[46:47], v[38:39], v[240:241], v[46:47]
	v_pk_fma_f32 v[98:99], v[36:37], v[88:89], v[98:99]
	v_pk_fma_f32 v[252:253], v[36:37], v[242:243], v[252:253]
	v_pk_fma_f32 v[62:63], v[34:35], v[90:91], v[62:63]
	v_pk_fma_f32 v[46:47], v[34:35], v[244:245], v[46:47]
	v_pk_fma_f32 v[98:99], v[32:33], v[92:93], v[98:99]
	v_pk_fma_f32 v[252:253], v[32:33], v[246:247], v[252:253]
	v_pk_fma_f32 v[62:63], v[40:41], v[94:95], v[62:63]
	v_pk_fma_f32 v[46:47], v[40:41], v[248:249], v[46:47]
	v_pk_fma_f32 v[98:99], v[42:43], v[96:97], v[98:99]
	v_pk_fma_f32 v[252:253], v[42:43], v[250:251], v[252:253]
	v_pk_add_f32 v[62:63], v[62:63], v[98:99]
	v_pk_add_f32 v[46:47], v[46:47], v[252:253]
	ds_read_b128 v[236:239], v65 offset:11776
	ds_read_b128 v[240:243], v65 offset:11792
	ds_read_b128 v[244:247], v65 offset:11808
	ds_read_b128 v[248:251], v65 offset:11824
	v_add_f32_e32 v62, v62, v63
	v_add_f32_e32 v46, v46, v47
	v_pk_mul_f32 v[30:31], v[30:31], v[16:17] op_sel:[0,1]
	v_pk_mul_f32 v[44:45], v[44:45], v[16:17] op_sel:[0,1]
	v_add_f32_dpp v62, v62, v62 quad_perm:[1,0,3,2] row_mask:0xf bank_mask:0xf bound_ctrl:1
	v_add_f32_dpp v46, v46, v46 quad_perm:[1,0,3,2] row_mask:0xf bank_mask:0xf bound_ctrl:1
	v_pk_mul_f32 v[38:39], v[38:39], v[16:17] op_sel:[0,1]
	v_pk_mul_f32 v[36:37], v[36:37], v[16:17] op_sel:[0,1]
	v_add_f32_dpp v62, v62, v62 quad_perm:[2,3,0,1] row_mask:0xf bank_mask:0xf bound_ctrl:1
	v_add_f32_dpp v46, v46, v46 quad_perm:[2,3,0,1] row_mask:0xf bank_mask:0xf bound_ctrl:1
	v_pk_mul_f32 v[34:35], v[34:35], v[16:17] op_sel:[0,1]
	v_pk_mul_f32 v[32:33], v[32:33], v[16:17] op_sel:[0,1]
	v_add_f32_dpp v62, v62, v62 row_half_mirror row_mask:0xf bank_mask:0xf bound_ctrl:1
	v_add_f32_dpp v46, v46, v46 row_half_mirror row_mask:0xf bank_mask:0xf bound_ctrl:1
	v_pk_mul_f32 v[40:41], v[40:41], v[16:17] op_sel:[0,1]
	v_pk_mul_f32 v[42:43], v[42:43], v[16:17] op_sel:[0,1]
	v_fma_f32 v63, -v17, v62, v61
	v_mul_f32_e32 v254, v11, v63
	global_store_dword v[28:29], v46, off
	v_pk_fma_f32 v[30:31], v[82:83], v[254:255], v[30:31] op_sel_hi:[1,0,1]
	v_pk_fma_f32 v[44:45], v[84:85], v[254:255], v[44:45] op_sel_hi:[1,0,1]
	v_pk_fma_f32 v[38:39], v[86:87], v[254:255], v[38:39] op_sel_hi:[1,0,1]
	v_pk_fma_f32 v[36:37], v[88:89], v[254:255], v[36:37] op_sel_hi:[1,0,1]
	v_pk_fma_f32 v[34:35], v[90:91], v[254:255], v[34:35] op_sel_hi:[1,0,1]
	v_pk_fma_f32 v[32:33], v[92:93], v[254:255], v[32:33] op_sel_hi:[1,0,1]
	v_pk_fma_f32 v[40:41], v[94:95], v[254:255], v[40:41] op_sel_hi:[1,0,1]
	v_pk_fma_f32 v[42:43], v[96:97], v[254:255], v[42:43] op_sel_hi:[1,0,1]
	ds_read_b128 v[14:17], v234 offset:96
	ds_read_b128 v[8:11], v234 offset:32
	ds_read_b32 v58, v100 offset:1024
	ds_read_b32 v59, v100 offset:1152
	ds_read_b32 v60, v100 offset:1280
	ds_read_b32 v61, v100 offset:1408
	ds_read_b128 v[82:85], v65 offset:4608
	ds_read_b128 v[86:89], v65 offset:4624
	ds_read_b128 v[90:93], v65 offset:4640
	ds_read_b128 v[94:97], v65 offset:4656
	s_waitcnt lgkmcnt(10)
; __device__ __forceinline__ void delta_scan_task(KP p, int l, bool samp, int b, int h, int cgp, float* sm) {
;     ...
;         for (int s0 = 0; s0 < nst; s0 += 4) {
; #pragma unroll
;             for (int s4 = 0; s4 < 4; ++s4) {
;                 const int s = s0 + s4;
;                 f32x2 k2[8], q2[8];
; #pragma unroll
;                 for (int hh = 0; hh < 4; ++hh) {
;                     const float4 a = *(const float4*)(bufp + s * 128 + ks * 16 + hh * 4);
;                     const float4 c = *(const float4*)(bufp + 2048 + s * 128 + ks * 16 + hh * 4);
;                     k2[2 * hh] = (f32x2){a.x, a.y}; k2[2 * hh + 1] = (f32x2){a.z, a.w};
;                     q2[2 * hh] = (f32x2){c.x, c.y}; q2[2 * hh + 1] = (f32x2){c.z, c.w};
;                 }
;                 const float vv = bufp[4096 + s * 32 + wid * 8 + cc];
;                 const float beta = bufp[4608 + s], alpha = bufp[4624 + s];
;                 f32x2 d0 = S[0] * k2[0], d1v = S[1] * k2[1], d2 = S[2] * k2[2], d3 = S[3] * k2[3];
;                 d0 = S[4] * k2[4] + d0; d1v = S[5] * k2[5] + d1v; d2 = S[6] * k2[6] + d2; d3 = S[7] * k2[7] + d3;
;                 d0 = (d0 + d1v) + (d2 + d3);
;                 const f32x2 al2 = (f32x2){alpha, alpha};
;                 f32x2 sa[8];
; #pragma unroll
;                 for (int j = 0; j < 8; ++j) sa[j] = S[j] * al2;
;                 const float dk = red8(d0.x + d0.y);
;                 const float vn = beta * (vv - alpha * dk);
;                 const f32x2 vn2 = (f32x2){vn, vn};
; #pragma unroll
;                 for (int j = 0; j < 8; ++j) S[j] = k2[j] * vn2 + sa[j];
;                 f32x2 o0 = S[0] * q2[0], o1 = S[1] * q2[1], o2 = S[2] * q2[2], o3 = S[3] * q2[3];
;                 o0 = S[4] * q2[4] + o0; o1 = S[5] * q2[5] + o1; o2 = S[6] * q2[6] + o2; o3 = S[7] * q2[7] + o3;
;                 o0 = (o0 + o1) + (o2 + o3);
;                 const float o = red8(o0.x + o0.y);
;                 oraw[(size_t)(row0 + tile * 16 + s) * 512 + h * 128 + e] = o;
;             }
	v_pk_mul_f32 v[62:63], v[30:31], v[66:67]
	v_pk_mul_f32 v[46:47], v[30:31], v[236:237]
	v_pk_mul_f32 v[98:99], v[44:45], v[68:69]
	v_pk_mul_f32 v[252:253], v[44:45], v[238:239]
	v_pk_fma_f32 v[62:63], v[38:39], v[70:71], v[62:63]
	v_pk_fma_f32 v[46:47], v[38:39], v[240:241], v[46:47]
	v_pk_fma_f32 v[98:99], v[36:37], v[72:73], v[98:99]
	v_pk_fma_f32 v[252:253], v[36:37], v[242:243], v[252:253]
	v_pk_fma_f32 v[62:63], v[34:35], v[74:75], v[62:63]
	v_pk_fma_f32 v[46:47], v[34:35], v[244:245], v[46:47]
	v_pk_fma_f32 v[98:99], v[32:33], v[76:77], v[98:99]
	v_pk_fma_f32 v[252:253], v[32:33], v[246:247], v[252:253]
	v_pk_fma_f32 v[62:63], v[40:41], v[78:79], v[62:63]
	v_pk_fma_f32 v[46:47], v[40:41], v[248:249], v[46:47]
	v_pk_fma_f32 v[98:99], v[42:43], v[80:81], v[98:99]
	v_pk_fma_f32 v[252:253], v[42:43], v[250:251], v[252:253]
	v_pk_add_f32 v[62:63], v[62:63], v[98:99]
	v_pk_add_f32 v[46:47], v[46:47], v[252:253]
	ds_read_b128 v[236:239], v65 offset:12288
	ds_read_b128 v[240:243], v65 offset:12304
	ds_read_b128 v[244:247], v65 offset:12320
	ds_read_b128 v[248:251], v65 offset:12336
	v_add_f32_e32 v62, v62, v63
	v_add_f32_e32 v46, v46, v47
	s_waitcnt lgkmcnt(4)
	v_pk_mul_f32 v[30:31], v[30:31], v[14:15] op_sel_hi:[1,0]
	v_pk_mul_f32 v[44:45], v[44:45], v[14:15] op_sel_hi:[1,0]
	v_add_f32_dpp v62, v62, v62 quad_perm:[1,0,3,2] row_mask:0xf bank_mask:0xf bound_ctrl:1
	v_add_f32_dpp v46, v46, v46 quad_perm:[1,0,3,2] row_mask:0xf bank_mask:0xf bound_ctrl:1
	v_pk_mul_f32 v[38:39], v[38:39], v[14:15] op_sel_hi:[1,0]
	v_pk_mul_f32 v[36:37], v[36:37], v[14:15] op_sel_hi:[1,0]
	v_add_f32_dpp v62, v62, v62 quad_perm:[2,3,0,1] row_mask:0xf bank_mask:0xf bound_ctrl:1
	v_add_f32_dpp v46, v46, v46 quad_perm:[2,3,0,1] row_mask:0xf bank_mask:0xf bound_ctrl:1
	v_pk_mul_f32 v[34:35], v[34:35], v[14:15] op_sel_hi:[1,0]
	v_pk_mul_f32 v[32:33], v[32:33], v[14:15] op_sel_hi:[1,0]
	v_add_f32_dpp v62, v62, v62 row_half_mirror row_mask:0xf bank_mask:0xf bound_ctrl:1
	v_add_f32_dpp v46, v46, v46 row_half_mirror row_mask:0xf bank_mask:0xf bound_ctrl:1
	v_pk_mul_f32 v[40:41], v[40:41], v[14:15] op_sel_hi:[1,0]
	v_pk_mul_f32 v[42:43], v[42:43], v[14:15] op_sel_hi:[1,0]
	v_fma_f32 v63, -v14, v62, v58
	v_mul_f32_e32 v254, v8, v63
	global_store_dword v[28:29], v46, off offset:2048
	v_lshl_add_u64 v[28:29], v[28:29], 0, s[20:21]
	v_pk_fma_f32 v[30:31], v[66:67], v[254:255], v[30:31] op_sel_hi:[1,0,1]
	v_pk_fma_f32 v[44:45], v[68:69], v[254:255], v[44:45] op_sel_hi:[1,0,1]
	v_pk_fma_f32 v[38:39], v[70:71], v[254:255], v[38:39] op_sel_hi:[1,0,1]
	v_pk_fma_f32 v[36:37], v[72:73], v[254:255], v[36:37] op_sel_hi:[1,0,1]
	v_pk_fma_f32 v[34:35], v[74:75], v[254:255], v[34:35] op_sel_hi:[1,0,1]
	v_pk_fma_f32 v[32:33], v[76:77], v[254:255], v[32:33] op_sel_hi:[1,0,1]
	v_pk_fma_f32 v[40:41], v[78:79], v[254:255], v[40:41] op_sel_hi:[1,0,1]
	v_pk_fma_f32 v[42:43], v[80:81], v[254:255], v[42:43] op_sel_hi:[1,0,1]
	ds_read_b128 v[66:69], v65 offset:5120
	ds_read_b128 v[70:73], v65 offset:5136
	ds_read_b128 v[74:77], v65 offset:5152
	ds_read_b128 v[78:81], v65 offset:5168
	v_pk_mul_f32 v[62:63], v[30:31], v[82:83]
	s_waitcnt lgkmcnt(4)
	v_pk_mul_f32 v[46:47], v[30:31], v[236:237]
	v_pk_mul_f32 v[98:99], v[44:45], v[84:85]
	v_pk_mul_f32 v[252:253], v[44:45], v[238:239]
	v_pk_fma_f32 v[62:63], v[38:39], v[86:87], v[62:63]
	v_pk_fma_f32 v[46:47], v[38:39], v[240:241], v[46:47]
	v_pk_fma_f32 v[98:99], v[36:37], v[88:89], v[98:99]
	v_pk_fma_f32 v[252:253], v[36:37], v[242:243], v[252:253]
	v_pk_fma_f32 v[62:63], v[34:35], v[90:91], v[62:63]
	v_pk_fma_f32 v[46:47], v[34:35], v[244:245], v[46:47]
	v_pk_fma_f32 v[98:99], v[32:33], v[92:93], v[98:99]
	v_pk_fma_f32 v[252:253], v[32:33], v[246:247], v[252:253]
	v_pk_fma_f32 v[62:63], v[40:41], v[94:95], v[62:63]
	v_pk_fma_f32 v[46:47], v[40:41], v[248:249], v[46:47]
	v_pk_fma_f32 v[98:99], v[42:43], v[96:97], v[98:99]
	v_pk_fma_f32 v[252:253], v[42:43], v[250:251], v[252:253]
	v_pk_add_f32 v[62:63], v[62:63], v[98:99]
	v_pk_add_f32 v[46:47], v[46:47], v[252:253]
	ds_read_b128 v[236:239], v65 offset:12800
	ds_read_b128 v[240:243], v65 offset:12816
	ds_read_b128 v[244:247], v65 offset:12832
	ds_read_b128 v[248:251], v65 offset:12848
	v_add_f32_e32 v62, v62, v63
	v_add_f32_e32 v46, v46, v47
	v_pk_mul_f32 v[30:31], v[30:31], v[14:15] op_sel:[0,1]
	v_pk_mul_f32 v[44:45], v[44:45], v[14:15] op_sel:[0,1]
	v_add_f32_dpp v62, v62, v62 quad_perm:[1,0,3,2] row_mask:0xf bank_mask:0xf bound_ctrl:1
	v_add_f32_dpp v46, v46, v46 quad_perm:[1,0,3,2] row_mask:0xf bank_mask:0xf bound_ctrl:1
	v_pk_mul_f32 v[38:39], v[38:39], v[14:15] op_sel:[0,1]
	v_pk_mul_f32 v[36:37], v[36:37], v[14:15] op_sel:[0,1]
	v_add_f32_dpp v62, v62, v62 quad_perm:[2,3,0,1] row_mask:0xf bank_mask:0xf bound_ctrl:1
	v_add_f32_dpp v46, v46, v46 quad_perm:[2,3,0,1] row_mask:0xf bank_mask:0xf bound_ctrl:1
	v_pk_mul_f32 v[34:35], v[34:35], v[14:15] op_sel:[0,1]
	v_pk_mul_f32 v[32:33], v[32:33], v[14:15] op_sel:[0,1]
	v_add_f32_dpp v62, v62, v62 row_half_mirror row_mask:0xf bank_mask:0xf bound_ctrl:1
	v_add_f32_dpp v46, v46, v46 row_half_mirror row_mask:0xf bank_mask:0xf bound_ctrl:1
	v_pk_mul_f32 v[40:41], v[40:41], v[14:15] op_sel:[0,1]
	v_pk_mul_f32 v[42:43], v[42:43], v[14:15] op_sel:[0,1]
	v_fma_f32 v63, -v15, v62, v59
	v_mul_f32_e32 v254, v9, v63
	global_store_dword v[28:29], v46, off offset:-4096
	v_pk_fma_f32 v[30:31], v[82:83], v[254:255], v[30:31] op_sel_hi:[1,0,1]
	v_pk_fma_f32 v[44:45], v[84:85], v[254:255], v[44:45] op_sel_hi:[1,0,1]
	v_pk_fma_f32 v[38:39], v[86:87], v[254:255], v[38:39] op_sel_hi:[1,0,1]
	v_pk_fma_f32 v[36:37], v[88:89], v[254:255], v[36:37] op_sel_hi:[1,0,1]
	v_pk_fma_f32 v[34:35], v[90:91], v[254:255], v[34:35] op_sel_hi:[1,0,1]
	v_pk_fma_f32 v[32:33], v[92:93], v[254:255], v[32:33] op_sel_hi:[1,0,1]
	v_pk_fma_f32 v[40:41], v[94:95], v[254:255], v[40:41] op_sel_hi:[1,0,1]
	v_pk_fma_f32 v[42:43], v[96:97], v[254:255], v[42:43] op_sel_hi:[1,0,1]
	ds_read_b128 v[82:85], v65 offset:5632
	ds_read_b128 v[86:89], v65 offset:5648
	ds_read_b128 v[90:93], v65 offset:5664
	ds_read_b128 v[94:97], v65 offset:5680
	s_waitcnt lgkmcnt(4)
; __device__ __forceinline__ void delta_scan_task(KP p, int l, bool samp, int b, int h, int cgp, float* sm) {
;     ...
;         for (int s0 = 0; s0 < nst; s0 += 4) {
; #pragma unroll
;             for (int s4 = 0; s4 < 4; ++s4) {
;                 const int s = s0 + s4;
;                 f32x2 k2[8], q2[8];
; #pragma unroll
;                 for (int hh = 0; hh < 4; ++hh) {
;                     const float4 a = *(const float4*)(bufp + s * 128 + ks * 16 + hh * 4);
;                     const float4 c = *(const float4*)(bufp + 2048 + s * 128 + ks * 16 + hh * 4);
;                     k2[2 * hh] = (f32x2){a.x, a.y}; k2[2 * hh + 1] = (f32x2){a.z, a.w};
;                     q2[2 * hh] = (f32x2){c.x, c.y}; q2[2 * hh + 1] = (f32x2){c.z, c.w};
;                 }
;                 const float vv = bufp[4096 + s * 32 + wid * 8 + cc];
;                 const float beta = bufp[4608 + s], alpha = bufp[4624 + s];
;                 f32x2 d0 = S[0] * k2[0], d1v = S[1] * k2[1], d2 = S[2] * k2[2], d3 = S[3] * k2[3];
;                 d0 = S[4] * k2[4] + d0; d1v = S[5] * k2[5] + d1v; d2 = S[6] * k2[6] + d2; d3 = S[7] * k2[7] + d3;
;                 d0 = (d0 + d1v) + (d2 + d3);
;                 const f32x2 al2 = (f32x2){alpha, alpha};
;                 f32x2 sa[8];
; #pragma unroll
;                 for (int j = 0; j < 8; ++j) sa[j] = S[j] * al2;
;                 const float dk = red8(d0.x + d0.y);
;                 const float vn = beta * (vv - alpha * dk);
;                 const f32x2 vn2 = (f32x2){vn, vn};
; #pragma unroll
;                 for (int j = 0; j < 8; ++j) S[j] = k2[j] * vn2 + sa[j];
;                 f32x2 o0 = S[0] * q2[0], o1 = S[1] * q2[1], o2 = S[2] * q2[2], o3 = S[3] * q2[3];
;                 o0 = S[4] * q2[4] + o0; o1 = S[5] * q2[5] + o1; o2 = S[6] * q2[6] + o2; o3 = S[7] * q2[7] + o3;
;                 o0 = (o0 + o1) + (o2 + o3);
;                 const float o = red8(o0.x + o0.y);
;                 oraw[(size_t)(row0 + tile * 16 + s) * 512 + h * 128 + e] = o;
;             }
	v_pk_mul_f32 v[62:63], v[30:31], v[66:67]
	v_pk_mul_f32 v[46:47], v[30:31], v[236:237]
	v_pk_mul_f32 v[98:99], v[44:45], v[68:69]
	v_pk_mul_f32 v[252:253], v[44:45], v[238:239]
	v_pk_fma_f32 v[62:63], v[38:39], v[70:71], v[62:63]
	v_pk_fma_f32 v[46:47], v[38:39], v[240:241], v[46:47]
	v_pk_fma_f32 v[98:99], v[36:37], v[72:73], v[98:99]
	v_pk_fma_f32 v[252:253], v[36:37], v[242:243], v[252:253]
	v_pk_fma_f32 v[62:63], v[34:35], v[74:75], v[62:63]
	v_pk_fma_f32 v[46:47], v[34:35], v[244:245], v[46:47]
	v_pk_fma_f32 v[98:99], v[32:33], v[76:77], v[98:99]
	v_pk_fma_f32 v[252:253], v[32:33], v[246:247], v[252:253]
	v_pk_fma_f32 v[62:63], v[40:41], v[78:79], v[62:63]
	v_pk_fma_f32 v[46:47], v[40:41], v[248:249], v[46:47]
	v_pk_fma_f32 v[98:99], v[42:43], v[80:81], v[98:99]
	v_pk_fma_f32 v[252:253], v[42:43], v[250:251], v[252:253]
	v_pk_add_f32 v[62:63], v[62:63], v[98:99]
	v_pk_add_f32 v[46:47], v[46:47], v[252:253]
	ds_read_b128 v[236:239], v65 offset:13312
	ds_read_b128 v[240:243], v65 offset:13328
	ds_read_b128 v[244:247], v65 offset:13344
	ds_read_b128 v[248:251], v65 offset:13360
	v_add_f32_e32 v62, v62, v63
	v_add_f32_e32 v46, v46, v47
	v_pk_mul_f32 v[30:31], v[30:31], v[16:17] op_sel_hi:[1,0]
	v_pk_mul_f32 v[44:45], v[44:45], v[16:17] op_sel_hi:[1,0]
	v_add_f32_dpp v62, v62, v62 quad_perm:[1,0,3,2] row_mask:0xf bank_mask:0xf bound_ctrl:1
	v_add_f32_dpp v46, v46, v46 quad_perm:[1,0,3,2] row_mask:0xf bank_mask:0xf bound_ctrl:1
	v_pk_mul_f32 v[38:39], v[38:39], v[16:17] op_sel_hi:[1,0]
	v_pk_mul_f32 v[36:37], v[36:37], v[16:17] op_sel_hi:[1,0]
	v_add_f32_dpp v62, v62, v62 quad_perm:[2,3,0,1] row_mask:0xf bank_mask:0xf bound_ctrl:1
	v_add_f32_dpp v46, v46, v46 quad_perm:[2,3,0,1] row_mask:0xf bank_mask:0xf bound_ctrl:1
	v_pk_mul_f32 v[34:35], v[34:35], v[16:17] op_sel_hi:[1,0]
	v_pk_mul_f32 v[32:33], v[32:33], v[16:17] op_sel_hi:[1,0]
	v_add_f32_dpp v62, v62, v62 row_half_mirror row_mask:0xf bank_mask:0xf bound_ctrl:1
	v_add_f32_dpp v46, v46, v46 row_half_mirror row_mask:0xf bank_mask:0xf bound_ctrl:1
	v_pk_mul_f32 v[40:41], v[40:41], v[16:17] op_sel_hi:[1,0]
	v_pk_mul_f32 v[42:43], v[42:43], v[16:17] op_sel_hi:[1,0]
	v_fma_f32 v63, -v16, v62, v60
	v_mul_f32_e32 v254, v10, v63
	global_store_dword v[28:29], v46, off offset:-2048
	v_pk_fma_f32 v[30:31], v[66:67], v[254:255], v[30:31] op_sel_hi:[1,0,1]
	v_pk_fma_f32 v[44:45], v[68:69], v[254:255], v[44:45] op_sel_hi:[1,0,1]
	v_pk_fma_f32 v[38:39], v[70:71], v[254:255], v[38:39] op_sel_hi:[1,0,1]
	v_pk_fma_f32 v[36:37], v[72:73], v[254:255], v[36:37] op_sel_hi:[1,0,1]
	v_pk_fma_f32 v[34:35], v[74:75], v[254:255], v[34:35] op_sel_hi:[1,0,1]
	v_pk_fma_f32 v[32:33], v[76:77], v[254:255], v[32:33] op_sel_hi:[1,0,1]
	v_pk_fma_f32 v[40:41], v[78:79], v[254:255], v[40:41] op_sel_hi:[1,0,1]
	v_pk_fma_f32 v[42:43], v[80:81], v[254:255], v[42:43] op_sel_hi:[1,0,1]
	ds_read_b128 v[66:69], v65 offset:6144
	ds_read_b128 v[70:73], v65 offset:6160
	ds_read_b128 v[74:77], v65 offset:6176
	ds_read_b128 v[78:81], v65 offset:6192
	s_waitcnt lgkmcnt(4)
	v_pk_mul_f32 v[62:63], v[30:31], v[82:83]
	v_pk_mul_f32 v[46:47], v[30:31], v[236:237]
	v_pk_mul_f32 v[98:99], v[44:45], v[84:85]
	v_pk_mul_f32 v[252:253], v[44:45], v[238:239]
	v_pk_fma_f32 v[62:63], v[38:39], v[86:87], v[62:63]
	v_pk_fma_f32 v[46:47], v[38:39], v[240:241], v[46:47]
	v_pk_fma_f32 v[98:99], v[36:37], v[88:89], v[98:99]
	v_pk_fma_f32 v[252:253], v[36:37], v[242:243], v[252:253]
	v_pk_fma_f32 v[62:63], v[34:35], v[90:91], v[62:63]
	v_pk_fma_f32 v[46:47], v[34:35], v[244:245], v[46:47]
	v_pk_fma_f32 v[98:99], v[32:33], v[92:93], v[98:99]
	v_pk_fma_f32 v[252:253], v[32:33], v[246:247], v[252:253]
	v_pk_fma_f32 v[62:63], v[40:41], v[94:95], v[62:63]
	v_pk_fma_f32 v[46:47], v[40:41], v[248:249], v[46:47]
	v_pk_fma_f32 v[98:99], v[42:43], v[96:97], v[98:99]
	v_pk_fma_f32 v[252:253], v[42:43], v[250:251], v[252:253]
	v_pk_add_f32 v[62:63], v[62:63], v[98:99]
	v_pk_add_f32 v[46:47], v[46:47], v[252:253]
	ds_read_b128 v[236:239], v65 offset:13824
	ds_read_b128 v[240:243], v65 offset:13840
	ds_read_b128 v[244:247], v65 offset:13856
	ds_read_b128 v[248:251], v65 offset:13872
	v_add_f32_e32 v62, v62, v63
	v_add_f32_e32 v46, v46, v47
	v_pk_mul_f32 v[30:31], v[30:31], v[16:17] op_sel:[0,1]
	v_pk_mul_f32 v[44:45], v[44:45], v[16:17] op_sel:[0,1]
	v_add_f32_dpp v62, v62, v62 quad_perm:[1,0,3,2] row_mask:0xf bank_mask:0xf bound_ctrl:1
	v_add_f32_dpp v46, v46, v46 quad_perm:[1,0,3,2] row_mask:0xf bank_mask:0xf bound_ctrl:1
	v_pk_mul_f32 v[38:39], v[38:39], v[16:17] op_sel:[0,1]
	v_pk_mul_f32 v[36:37], v[36:37], v[16:17] op_sel:[0,1]
	v_add_f32_dpp v62, v62, v62 quad_perm:[2,3,0,1] row_mask:0xf bank_mask:0xf bound_ctrl:1
	v_add_f32_dpp v46, v46, v46 quad_perm:[2,3,0,1] row_mask:0xf bank_mask:0xf bound_ctrl:1
	v_pk_mul_f32 v[34:35], v[34:35], v[16:17] op_sel:[0,1]
	v_pk_mul_f32 v[32:33], v[32:33], v[16:17] op_sel:[0,1]
	v_add_f32_dpp v62, v62, v62 row_half_mirror row_mask:0xf bank_mask:0xf bound_ctrl:1
	v_add_f32_dpp v46, v46, v46 row_half_mirror row_mask:0xf bank_mask:0xf bound_ctrl:1
	v_pk_mul_f32 v[40:41], v[40:41], v[16:17] op_sel:[0,1]
	v_pk_mul_f32 v[42:43], v[42:43], v[16:17] op_sel:[0,1]
	v_fma_f32 v63, -v17, v62, v61
	v_mul_f32_e32 v254, v11, v63
	global_store_dword v[28:29], v46, off
	v_pk_fma_f32 v[30:31], v[82:83], v[254:255], v[30:31] op_sel_hi:[1,0,1]
	v_pk_fma_f32 v[44:45], v[84:85], v[254:255], v[44:45] op_sel_hi:[1,0,1]
	v_pk_fma_f32 v[38:39], v[86:87], v[254:255], v[38:39] op_sel_hi:[1,0,1]
	v_pk_fma_f32 v[36:37], v[88:89], v[254:255], v[36:37] op_sel_hi:[1,0,1]
	v_pk_fma_f32 v[34:35], v[90:91], v[254:255], v[34:35] op_sel_hi:[1,0,1]
	v_pk_fma_f32 v[32:33], v[92:93], v[254:255], v[32:33] op_sel_hi:[1,0,1]
	v_pk_fma_f32 v[40:41], v[94:95], v[254:255], v[40:41] op_sel_hi:[1,0,1]
	v_pk_fma_f32 v[42:43], v[96:97], v[254:255], v[42:43] op_sel_hi:[1,0,1]
	ds_read_b128 v[14:17], v234 offset:112
	ds_read_b128 v[8:11], v234 offset:48
	ds_read_b32 v58, v100 offset:1536
	ds_read_b32 v59, v100 offset:1664
	ds_read_b32 v60, v100 offset:1792
	ds_read_b32 v61, v100 offset:1920
	ds_read_b128 v[82:85], v65 offset:6656
	ds_read_b128 v[86:89], v65 offset:6672
	ds_read_b128 v[90:93], v65 offset:6688
	ds_read_b128 v[94:97], v65 offset:6704
	s_waitcnt lgkmcnt(10)
; __device__ __forceinline__ void delta_scan_task(KP p, int l, bool samp, int b, int h, int cgp, float* sm) {
;     ...
;         for (int s0 = 0; s0 < nst; s0 += 4) {
; #pragma unroll
;             for (int s4 = 0; s4 < 4; ++s4) {
;                 const int s = s0 + s4;
;                 f32x2 k2[8], q2[8];
; #pragma unroll
;                 for (int hh = 0; hh < 4; ++hh) {
;                     const float4 a = *(const float4*)(bufp + s * 128 + ks * 16 + hh * 4);
;                     const float4 c = *(const float4*)(bufp + 2048 + s * 128 + ks * 16 + hh * 4);
;                     k2[2 * hh] = (f32x2){a.x, a.y}; k2[2 * hh + 1] = (f32x2){a.z, a.w};
;                     q2[2 * hh] = (f32x2){c.x, c.y}; q2[2 * hh + 1] = (f32x2){c.z, c.w};
;                 }
;                 const float vv = bufp[4096 + s * 32 + wid * 8 + cc];
;                 const float beta = bufp[4608 + s], alpha = bufp[4624 + s];
;                 f32x2 d0 = S[0] * k2[0], d1v = S[1] * k2[1], d2 = S[2] * k2[2], d3 = S[3] * k2[3];
;                 d0 = S[4] * k2[4] + d0; d1v = S[5] * k2[5] + d1v; d2 = S[6] * k2[6] + d2; d3 = S[7] * k2[7] + d3;
;                 d0 = (d0 + d1v) + (d2 + d3);
;                 const f32x2 al2 = (f32x2){alpha, alpha};
;                 f32x2 sa[8];
; #pragma unroll
;                 for (int j = 0; j < 8; ++j) sa[j] = S[j] * al2;
;                 const float dk = red8(d0.x + d0.y);
;                 const float vn = beta * (vv - alpha * dk);
;                 const f32x2 vn2 = (f32x2){vn, vn};
; #pragma unroll
;                 for (int j = 0; j < 8; ++j) S[j] = k2[j] * vn2 + sa[j];
;                 f32x2 o0 = S[0] * q2[0], o1 = S[1] * q2[1], o2 = S[2] * q2[2], o3 = S[3] * q2[3];
;                 o0 = S[4] * q2[4] + o0; o1 = S[5] * q2[5] + o1; o2 = S[6] * q2[6] + o2; o3 = S[7] * q2[7] + o3;
;                 o0 = (o0 + o1) + (o2 + o3);
;                 const float o = red8(o0.x + o0.y);
;                 oraw[(size_t)(row0 + tile * 16 + s) * 512 + h * 128 + e] = o;
;             }
	v_pk_mul_f32 v[62:63], v[30:31], v[66:67]
	v_pk_mul_f32 v[46:47], v[30:31], v[236:237]
	v_pk_mul_f32 v[98:99], v[44:45], v[68:69]
	v_pk_mul_f32 v[252:253], v[44:45], v[238:239]
	v_pk_fma_f32 v[62:63], v[38:39], v[70:71], v[62:63]
	v_pk_fma_f32 v[46:47], v[38:39], v[240:241], v[46:47]
	v_pk_fma_f32 v[98:99], v[36:37], v[72:73], v[98:99]
	v_pk_fma_f32 v[252:253], v[36:37], v[242:243], v[252:253]
	v_pk_fma_f32 v[62:63], v[34:35], v[74:75], v[62:63]
	v_pk_fma_f32 v[46:47], v[34:35], v[244:245], v[46:47]
	v_pk_fma_f32 v[98:99], v[32:33], v[76:77], v[98:99]
	v_pk_fma_f32 v[252:253], v[32:33], v[246:247], v[252:253]
	v_pk_fma_f32 v[62:63], v[40:41], v[78:79], v[62:63]
	v_pk_fma_f32 v[46:47], v[40:41], v[248:249], v[46:47]
	v_pk_fma_f32 v[98:99], v[42:43], v[80:81], v[98:99]
	v_pk_fma_f32 v[252:253], v[42:43], v[250:251], v[252:253]
	v_pk_add_f32 v[62:63], v[62:63], v[98:99]
	v_pk_add_f32 v[46:47], v[46:47], v[252:253]
	ds_read_b128 v[236:239], v65 offset:14336
	ds_read_b128 v[240:243], v65 offset:14352
	ds_read_b128 v[244:247], v65 offset:14368
	ds_read_b128 v[248:251], v65 offset:14384
	v_add_f32_e32 v62, v62, v63
	v_add_f32_e32 v46, v46, v47
	s_waitcnt lgkmcnt(4)
	v_pk_mul_f32 v[30:31], v[30:31], v[14:15] op_sel_hi:[1,0]
	v_pk_mul_f32 v[44:45], v[44:45], v[14:15] op_sel_hi:[1,0]
	v_add_f32_dpp v62, v62, v62 quad_perm:[1,0,3,2] row_mask:0xf bank_mask:0xf bound_ctrl:1
	v_add_f32_dpp v46, v46, v46 quad_perm:[1,0,3,2] row_mask:0xf bank_mask:0xf bound_ctrl:1
	v_pk_mul_f32 v[38:39], v[38:39], v[14:15] op_sel_hi:[1,0]
	v_pk_mul_f32 v[36:37], v[36:37], v[14:15] op_sel_hi:[1,0]
	v_add_f32_dpp v62, v62, v62 quad_perm:[2,3,0,1] row_mask:0xf bank_mask:0xf bound_ctrl:1
	v_add_f32_dpp v46, v46, v46 quad_perm:[2,3,0,1] row_mask:0xf bank_mask:0xf bound_ctrl:1
	v_pk_mul_f32 v[34:35], v[34:35], v[14:15] op_sel_hi:[1,0]
	v_pk_mul_f32 v[32:33], v[32:33], v[14:15] op_sel_hi:[1,0]
	v_add_f32_dpp v62, v62, v62 row_half_mirror row_mask:0xf bank_mask:0xf bound_ctrl:1
	v_add_f32_dpp v46, v46, v46 row_half_mirror row_mask:0xf bank_mask:0xf bound_ctrl:1
	v_pk_mul_f32 v[40:41], v[40:41], v[14:15] op_sel_hi:[1,0]
	v_pk_mul_f32 v[42:43], v[42:43], v[14:15] op_sel_hi:[1,0]
	v_fma_f32 v63, -v14, v62, v58
	v_mul_f32_e32 v254, v8, v63
	global_store_dword v[28:29], v46, off offset:2048
	v_lshl_add_u64 v[28:29], v[28:29], 0, s[20:21]
	v_pk_fma_f32 v[30:31], v[66:67], v[254:255], v[30:31] op_sel_hi:[1,0,1]
	v_pk_fma_f32 v[44:45], v[68:69], v[254:255], v[44:45] op_sel_hi:[1,0,1]
	v_pk_fma_f32 v[38:39], v[70:71], v[254:255], v[38:39] op_sel_hi:[1,0,1]
	v_pk_fma_f32 v[36:37], v[72:73], v[254:255], v[36:37] op_sel_hi:[1,0,1]
	v_pk_fma_f32 v[34:35], v[74:75], v[254:255], v[34:35] op_sel_hi:[1,0,1]
	v_pk_fma_f32 v[32:33], v[76:77], v[254:255], v[32:33] op_sel_hi:[1,0,1]
	v_pk_fma_f32 v[40:41], v[78:79], v[254:255], v[40:41] op_sel_hi:[1,0,1]
	v_pk_fma_f32 v[42:43], v[80:81], v[254:255], v[42:43] op_sel_hi:[1,0,1]
	ds_read_b128 v[66:69], v65 offset:7168
	ds_read_b128 v[70:73], v65 offset:7184
	ds_read_b128 v[74:77], v65 offset:7200
	ds_read_b128 v[78:81], v65 offset:7216
	v_pk_mul_f32 v[62:63], v[30:31], v[82:83]
	s_waitcnt lgkmcnt(4)
	v_pk_mul_f32 v[46:47], v[30:31], v[236:237]
	v_pk_mul_f32 v[98:99], v[44:45], v[84:85]
	v_pk_mul_f32 v[252:253], v[44:45], v[238:239]
	v_pk_fma_f32 v[62:63], v[38:39], v[86:87], v[62:63]
	v_pk_fma_f32 v[46:47], v[38:39], v[240:241], v[46:47]
	v_pk_fma_f32 v[98:99], v[36:37], v[88:89], v[98:99]
	v_pk_fma_f32 v[252:253], v[36:37], v[242:243], v[252:253]
	v_pk_fma_f32 v[62:63], v[34:35], v[90:91], v[62:63]
	v_pk_fma_f32 v[46:47], v[34:35], v[244:245], v[46:47]
	v_pk_fma_f32 v[98:99], v[32:33], v[92:93], v[98:99]
	v_pk_fma_f32 v[252:253], v[32:33], v[246:247], v[252:253]
	v_pk_fma_f32 v[62:63], v[40:41], v[94:95], v[62:63]
	v_pk_fma_f32 v[46:47], v[40:41], v[248:249], v[46:47]
	v_pk_fma_f32 v[98:99], v[42:43], v[96:97], v[98:99]
	v_pk_fma_f32 v[252:253], v[42:43], v[250:251], v[252:253]
	v_pk_add_f32 v[62:63], v[62:63], v[98:99]
	v_pk_add_f32 v[46:47], v[46:47], v[252:253]
	ds_read_b128 v[236:239], v65 offset:14848
	ds_read_b128 v[240:243], v65 offset:14864
	ds_read_b128 v[244:247], v65 offset:14880
	ds_read_b128 v[248:251], v65 offset:14896
	v_add_f32_e32 v62, v62, v63
	v_add_f32_e32 v46, v46, v47
	v_pk_mul_f32 v[30:31], v[30:31], v[14:15] op_sel:[0,1]
	v_pk_mul_f32 v[44:45], v[44:45], v[14:15] op_sel:[0,1]
	v_add_f32_dpp v62, v62, v62 quad_perm:[1,0,3,2] row_mask:0xf bank_mask:0xf bound_ctrl:1
	v_add_f32_dpp v46, v46, v46 quad_perm:[1,0,3,2] row_mask:0xf bank_mask:0xf bound_ctrl:1
	v_pk_mul_f32 v[38:39], v[38:39], v[14:15] op_sel:[0,1]
	v_pk_mul_f32 v[36:37], v[36:37], v[14:15] op_sel:[0,1]
	v_add_f32_dpp v62, v62, v62 quad_perm:[2,3,0,1] row_mask:0xf bank_mask:0xf bound_ctrl:1
	v_add_f32_dpp v46, v46, v46 quad_perm:[2,3,0,1] row_mask:0xf bank_mask:0xf bound_ctrl:1
	v_pk_mul_f32 v[34:35], v[34:35], v[14:15] op_sel:[0,1]
	v_pk_mul_f32 v[32:33], v[32:33], v[14:15] op_sel:[0,1]
	v_add_f32_dpp v62, v62, v62 row_half_mirror row_mask:0xf bank_mask:0xf bound_ctrl:1
	v_add_f32_dpp v46, v46, v46 row_half_mirror row_mask:0xf bank_mask:0xf bound_ctrl:1
	v_pk_mul_f32 v[40:41], v[40:41], v[14:15] op_sel:[0,1]
	v_pk_mul_f32 v[42:43], v[42:43], v[14:15] op_sel:[0,1]
	v_fma_f32 v63, -v15, v62, v59
	v_mul_f32_e32 v254, v9, v63
	global_store_dword v[28:29], v46, off offset:-4096
	v_pk_fma_f32 v[30:31], v[82:83], v[254:255], v[30:31] op_sel_hi:[1,0,1]
	v_pk_fma_f32 v[44:45], v[84:85], v[254:255], v[44:45] op_sel_hi:[1,0,1]
	v_pk_fma_f32 v[38:39], v[86:87], v[254:255], v[38:39] op_sel_hi:[1,0,1]
	v_pk_fma_f32 v[36:37], v[88:89], v[254:255], v[36:37] op_sel_hi:[1,0,1]
	v_pk_fma_f32 v[34:35], v[90:91], v[254:255], v[34:35] op_sel_hi:[1,0,1]
	v_pk_fma_f32 v[32:33], v[92:93], v[254:255], v[32:33] op_sel_hi:[1,0,1]
	v_pk_fma_f32 v[40:41], v[94:95], v[254:255], v[40:41] op_sel_hi:[1,0,1]
	v_pk_fma_f32 v[42:43], v[96:97], v[254:255], v[42:43] op_sel_hi:[1,0,1]
	ds_read_b128 v[82:85], v65 offset:7680
	ds_read_b128 v[86:89], v65 offset:7696
	ds_read_b128 v[90:93], v65 offset:7712
	ds_read_b128 v[94:97], v65 offset:7728
	s_waitcnt lgkmcnt(4)
; __device__ __forceinline__ void delta_scan_task(KP p, int l, bool samp, int b, int h, int cgp, float* sm) {
;     ...
;         for (int s0 = 0; s0 < nst; s0 += 4) {
; #pragma unroll
;             for (int s4 = 0; s4 < 4; ++s4) {
;                 const int s = s0 + s4;
;                 f32x2 k2[8], q2[8];
; #pragma unroll
;                 for (int hh = 0; hh < 4; ++hh) {
;                     const float4 a = *(const float4*)(bufp + s * 128 + ks * 16 + hh * 4);
;                     const float4 c = *(const float4*)(bufp + 2048 + s * 128 + ks * 16 + hh * 4);
;                     k2[2 * hh] = (f32x2){a.x, a.y}; k2[2 * hh + 1] = (f32x2){a.z, a.w};
;                     q2[2 * hh] = (f32x2){c.x, c.y}; q2[2 * hh + 1] = (f32x2){c.z, c.w};
;                 }
;                 const float vv = bufp[4096 + s * 32 + wid * 8 + cc];
;                 const float beta = bufp[4608 + s], alpha = bufp[4624 + s];
;                 f32x2 d0 = S[0] * k2[0], d1v = S[1] * k2[1], d2 = S[2] * k2[2], d3 = S[3] * k2[3];
;                 d0 = S[4] * k2[4] + d0; d1v = S[5] * k2[5] + d1v; d2 = S[6] * k2[6] + d2; d3 = S[7] * k2[7] + d3;
;                 d0 = (d0 + d1v) + (d2 + d3);
;                 const f32x2 al2 = (f32x2){alpha, alpha};
;                 f32x2 sa[8];
; #pragma unroll
;                 for (int j = 0; j < 8; ++j) sa[j] = S[j] * al2;
;                 const float dk = red8(d0.x + d0.y);
;                 const float vn = beta * (vv - alpha * dk);
;                 const f32x2 vn2 = (f32x2){vn, vn};
; #pragma unroll
;                 for (int j = 0; j < 8; ++j) S[j] = k2[j] * vn2 + sa[j];
;                 f32x2 o0 = S[0] * q2[0], o1 = S[1] * q2[1], o2 = S[2] * q2[2], o3 = S[3] * q2[3];
;                 o0 = S[4] * q2[4] + o0; o1 = S[5] * q2[5] + o1; o2 = S[6] * q2[6] + o2; o3 = S[7] * q2[7] + o3;
;                 o0 = (o0 + o1) + (o2 + o3);
;                 const float o = red8(o0.x + o0.y);
;                 oraw[(size_t)(row0 + tile * 16 + s) * 512 + h * 128 + e] = o;
;             }
	v_pk_mul_f32 v[62:63], v[30:31], v[66:67]
	v_pk_mul_f32 v[46:47], v[30:31], v[236:237]
	v_pk_mul_f32 v[98:99], v[44:45], v[68:69]
	v_pk_mul_f32 v[252:253], v[44:45], v[238:239]
	v_pk_fma_f32 v[62:63], v[38:39], v[70:71], v[62:63]
	v_pk_fma_f32 v[46:47], v[38:39], v[240:241], v[46:47]
	v_pk_fma_f32 v[98:99], v[36:37], v[72:73], v[98:99]
	v_pk_fma_f32 v[252:253], v[36:37], v[242:243], v[252:253]
	v_pk_fma_f32 v[62:63], v[34:35], v[74:75], v[62:63]
	v_pk_fma_f32 v[46:47], v[34:35], v[244:245], v[46:47]
	v_pk_fma_f32 v[98:99], v[32:33], v[76:77], v[98:99]
	v_pk_fma_f32 v[252:253], v[32:33], v[246:247], v[252:253]
	v_pk_fma_f32 v[62:63], v[40:41], v[78:79], v[62:63]
	v_pk_fma_f32 v[46:47], v[40:41], v[248:249], v[46:47]
	v_pk_fma_f32 v[98:99], v[42:43], v[80:81], v[98:99]
	v_pk_fma_f32 v[252:253], v[42:43], v[250:251], v[252:253]
	v_pk_add_f32 v[62:63], v[62:63], v[98:99]
	v_pk_add_f32 v[46:47], v[46:47], v[252:253]
	ds_read_b128 v[236:239], v65 offset:15360
	ds_read_b128 v[240:243], v65 offset:15376
	ds_read_b128 v[244:247], v65 offset:15392
	ds_read_b128 v[248:251], v65 offset:15408
	v_add_f32_e32 v62, v62, v63
	v_add_f32_e32 v46, v46, v47
	v_pk_mul_f32 v[30:31], v[30:31], v[16:17] op_sel_hi:[1,0]
	v_pk_mul_f32 v[44:45], v[44:45], v[16:17] op_sel_hi:[1,0]
	v_add_f32_dpp v62, v62, v62 quad_perm:[1,0,3,2] row_mask:0xf bank_mask:0xf bound_ctrl:1
	v_add_f32_dpp v46, v46, v46 quad_perm:[1,0,3,2] row_mask:0xf bank_mask:0xf bound_ctrl:1
	v_pk_mul_f32 v[38:39], v[38:39], v[16:17] op_sel_hi:[1,0]
	v_pk_mul_f32 v[36:37], v[36:37], v[16:17] op_sel_hi:[1,0]
	v_add_f32_dpp v62, v62, v62 quad_perm:[2,3,0,1] row_mask:0xf bank_mask:0xf bound_ctrl:1
	v_add_f32_dpp v46, v46, v46 quad_perm:[2,3,0,1] row_mask:0xf bank_mask:0xf bound_ctrl:1
	v_pk_mul_f32 v[34:35], v[34:35], v[16:17] op_sel_hi:[1,0]
	v_pk_mul_f32 v[32:33], v[32:33], v[16:17] op_sel_hi:[1,0]
	v_add_f32_dpp v62, v62, v62 row_half_mirror row_mask:0xf bank_mask:0xf bound_ctrl:1
	v_add_f32_dpp v46, v46, v46 row_half_mirror row_mask:0xf bank_mask:0xf bound_ctrl:1
	v_pk_mul_f32 v[40:41], v[40:41], v[16:17] op_sel_hi:[1,0]
	v_pk_mul_f32 v[42:43], v[42:43], v[16:17] op_sel_hi:[1,0]
	v_fma_f32 v63, -v16, v62, v60
	v_mul_f32_e32 v254, v10, v63
	global_store_dword v[28:29], v46, off offset:-2048
	v_pk_fma_f32 v[30:31], v[66:67], v[254:255], v[30:31] op_sel_hi:[1,0,1]
	v_pk_fma_f32 v[44:45], v[68:69], v[254:255], v[44:45] op_sel_hi:[1,0,1]
	v_pk_fma_f32 v[38:39], v[70:71], v[254:255], v[38:39] op_sel_hi:[1,0,1]
	v_pk_fma_f32 v[36:37], v[72:73], v[254:255], v[36:37] op_sel_hi:[1,0,1]
	v_pk_fma_f32 v[34:35], v[74:75], v[254:255], v[34:35] op_sel_hi:[1,0,1]
	v_pk_fma_f32 v[32:33], v[76:77], v[254:255], v[32:33] op_sel_hi:[1,0,1]
	v_pk_fma_f32 v[40:41], v[78:79], v[254:255], v[40:41] op_sel_hi:[1,0,1]
	v_pk_fma_f32 v[42:43], v[80:81], v[254:255], v[42:43] op_sel_hi:[1,0,1]
	s_waitcnt lgkmcnt(0)
	v_pk_mul_f32 v[62:63], v[30:31], v[82:83]
	v_pk_mul_f32 v[46:47], v[30:31], v[236:237]
	v_pk_mul_f32 v[98:99], v[44:45], v[84:85]
	v_pk_mul_f32 v[252:253], v[44:45], v[238:239]
	v_pk_fma_f32 v[62:63], v[38:39], v[86:87], v[62:63]
	v_pk_fma_f32 v[46:47], v[38:39], v[240:241], v[46:47]
	v_pk_fma_f32 v[98:99], v[36:37], v[88:89], v[98:99]
	v_pk_fma_f32 v[252:253], v[36:37], v[242:243], v[252:253]
	v_pk_fma_f32 v[62:63], v[34:35], v[90:91], v[62:63]
	v_pk_fma_f32 v[46:47], v[34:35], v[244:245], v[46:47]
	v_pk_fma_f32 v[98:99], v[32:33], v[92:93], v[98:99]
	v_pk_fma_f32 v[252:253], v[32:33], v[246:247], v[252:253]
	v_pk_fma_f32 v[62:63], v[40:41], v[94:95], v[62:63]
	v_pk_fma_f32 v[46:47], v[40:41], v[248:249], v[46:47]
	v_pk_fma_f32 v[98:99], v[42:43], v[96:97], v[98:99]
	v_pk_fma_f32 v[252:253], v[42:43], v[250:251], v[252:253]
	v_pk_add_f32 v[62:63], v[62:63], v[98:99]
	v_pk_add_f32 v[46:47], v[46:47], v[252:253]
	ds_read_b128 v[236:239], v65 offset:15872
	ds_read_b128 v[240:243], v65 offset:15888
	ds_read_b128 v[244:247], v65 offset:15904
	ds_read_b128 v[248:251], v65 offset:15920
	v_add_f32_e32 v62, v62, v63
	v_add_f32_e32 v46, v46, v47
	v_pk_mul_f32 v[30:31], v[30:31], v[16:17] op_sel:[0,1]
	v_pk_mul_f32 v[44:45], v[44:45], v[16:17] op_sel:[0,1]
	v_add_f32_dpp v62, v62, v62 quad_perm:[1,0,3,2] row_mask:0xf bank_mask:0xf bound_ctrl:1
	v_add_f32_dpp v46, v46, v46 quad_perm:[1,0,3,2] row_mask:0xf bank_mask:0xf bound_ctrl:1
	v_pk_mul_f32 v[38:39], v[38:39], v[16:17] op_sel:[0,1]
	v_pk_mul_f32 v[36:37], v[36:37], v[16:17] op_sel:[0,1]
	v_add_f32_dpp v62, v62, v62 quad_perm:[2,3,0,1] row_mask:0xf bank_mask:0xf bound_ctrl:1
	v_add_f32_dpp v46, v46, v46 quad_perm:[2,3,0,1] row_mask:0xf bank_mask:0xf bound_ctrl:1
	v_pk_mul_f32 v[34:35], v[34:35], v[16:17] op_sel:[0,1]
	v_pk_mul_f32 v[32:33], v[32:33], v[16:17] op_sel:[0,1]
	v_add_f32_dpp v62, v62, v62 row_half_mirror row_mask:0xf bank_mask:0xf bound_ctrl:1
	v_add_f32_dpp v46, v46, v46 row_half_mirror row_mask:0xf bank_mask:0xf bound_ctrl:1
	v_pk_mul_f32 v[40:41], v[40:41], v[16:17] op_sel:[0,1]
	v_pk_mul_f32 v[42:43], v[42:43], v[16:17] op_sel:[0,1]
	v_fma_f32 v63, -v17, v62, v61
	v_mul_f32_e32 v254, v11, v63
	global_store_dword v[28:29], v46, off
	v_pk_fma_f32 v[30:31], v[82:83], v[254:255], v[30:31] op_sel_hi:[1,0,1]
	v_pk_fma_f32 v[44:45], v[84:85], v[254:255], v[44:45] op_sel_hi:[1,0,1]
	v_pk_fma_f32 v[38:39], v[86:87], v[254:255], v[38:39] op_sel_hi:[1,0,1]
	v_pk_fma_f32 v[36:37], v[88:89], v[254:255], v[36:37] op_sel_hi:[1,0,1]
	v_pk_fma_f32 v[34:35], v[90:91], v[254:255], v[34:35] op_sel_hi:[1,0,1]
	v_pk_fma_f32 v[32:33], v[92:93], v[254:255], v[32:33] op_sel_hi:[1,0,1]
	v_pk_fma_f32 v[40:41], v[94:95], v[254:255], v[40:41] op_sel_hi:[1,0,1]
	v_pk_fma_f32 v[42:43], v[96:97], v[254:255], v[42:43] op_sel_hi:[1,0,1]
	s_waitcnt lgkmcnt(0)
	v_pk_mul_f32 v[46:47], v[30:31], v[236:237]
	v_pk_mul_f32 v[252:253], v[44:45], v[238:239]
	v_pk_fma_f32 v[46:47], v[38:39], v[240:241], v[46:47]
	v_pk_fma_f32 v[252:253], v[36:37], v[242:243], v[252:253]
	v_pk_fma_f32 v[46:47], v[34:35], v[244:245], v[46:47]
	v_pk_fma_f32 v[252:253], v[32:33], v[246:247], v[252:253]
	v_pk_fma_f32 v[46:47], v[40:41], v[248:249], v[46:47]
	v_pk_fma_f32 v[252:253], v[42:43], v[250:251], v[252:253]
	s_nop 0
	v_pk_add_f32 v[46:47], v[46:47], v[252:253]
	s_nop 0
	v_add_f32_e32 v46, v46, v47
	s_nop 1
	v_add_f32_dpp v46, v46, v46 quad_perm:[1,0,3,2] row_mask:0xf bank_mask:0xf bound_ctrl:1
	s_nop 1
	v_add_f32_dpp v46, v46, v46 quad_perm:[2,3,0,1] row_mask:0xf bank_mask:0xf bound_ctrl:1
	s_nop 1
	v_add_f32_dpp v46, v46, v46 row_half_mirror row_mask:0xf bank_mask:0xf bound_ctrl:1
	global_store_dword v[28:29], v46, off offset:2048
	s_mov_b64 s[12:13], 0x8000
	v_lshl_add_u64 v[26:27], v[26:27], 0, s[12:13]
	s_cmpk_eq_i32 s42, 0x80
	s_mov_b32 s2, s42
	s_cbranch_scc0 .LBB0_139
; __device__ __forceinline__ void delta_scan_task(KP p, int l, bool samp, int b, int h, int cgp, float* sm) {
;     ...
;     float* so = (samp ? p->out + O_SDELTA : p->out + O_PDELTA) + sbase;
; #pragma unroll
;     for (int j = 0; j < 8; ++j) {
;         __builtin_nontemporal_store(S[j].x, so + (size_t)(ks * 16 + 2 * j) * 128 + e);
;         __builtin_nontemporal_store(S[j].y, so + (size_t)(ks * 16 + 2 * j + 1) * 128 + e);
;     }
;     __syncthreads();
	v_readlane_b32 s12, v230, 25
	s_lshl_b32 s2, s12, 5
	v_readlane_b32 s11, v233, 18
	v_readlane_b32 s13, v230, 26
	s_add_i32 s12, s2, s11
	s_ashr_i32 s13, s12, 31
	s_lshl_b64 s[12:13], s[12:13], 16
	s_add_u32 s12, s56, s12
	v_or_b32_e32 v0, v52, v51
	s_addc_u32 s13, s57, s13
	v_lshlrev_b32_e32 v2, 13, v19
	v_mov_b32_e32 v3, v13
	v_ashrrev_i32_e32 v1, 31, v0
	v_lshl_add_u64 v[2:3], s[12:13], 0, v[2:3]
	v_lshl_add_u64 v[0:1], v[0:1], 2, v[2:3]
	s_mov_b64 s[12:13], 0x4928000
	s_mov_b32 s2, 0x4929000
	v_lshl_add_u64 v[2:3], v[0:1], 0, s[12:13]
	v_add_co_u32_e32 v0, vcc, s2, v0
	s_mov_b64 s[12:13], 0
	s_nop 0
	v_addc_co_u32_e32 v1, vcc, 0, v1, vcc
	global_store_dword v[0:1], v30, off offset:-4096 nt
	global_store_dword v[2:3], v31, off offset:512 nt
	global_store_dword v[2:3], v44, off offset:1024 nt
	global_store_dword v[2:3], v45, off offset:1536 nt
	global_store_dword v[2:3], v38, off offset:2048 nt
	global_store_dword v[2:3], v39, off offset:2560 nt
	global_store_dword v[2:3], v36, off offset:3072 nt
	global_store_dword v[2:3], v37, off offset:3584 nt
	global_store_dword v[0:1], v34, off nt
	global_store_dword v[0:1], v35, off offset:512 nt
	global_store_dword v[0:1], v32, off offset:1024 nt
	global_store_dword v[0:1], v33, off offset:1536 nt
	global_store_dword v[0:1], v40, off offset:2048 nt
	global_store_dword v[0:1], v41, off offset:2560 nt
	global_store_dword v[0:1], v42, off offset:3072 nt
	global_store_dword v[0:1], v43, off offset:3584 nt
	s_barrier

; __device__ __forceinline__ void rwkv_scan_task(KP p, int l, bool samp, int b, int h, int hb, float* sm) {
;     ...
;         for (int s0 = 0; s0 < nst; s0 += 4) {
; #pragma unroll
;             for (int s4 = 0; s4 < 4; ++s4) {
;                 const int s = s0 + s4;
;                 const float* bs = bufp + s * 64 + ks * 8;
;                 f32x2 w2[4], kk2[4], ka2[4], kp2[4], r2[4];
; #pragma unroll
;                 for (int hh = 0; hh < 2; ++hh) {
;                     const float4 a = *(const float4*)(bs + hh * 4);
;                     const float4 bq = *(const float4*)(bs + 1024 + hh * 4);
;                     const float4 c = *(const float4*)(bs + 2048 + hh * 4);
;                     const float4 d = *(const float4*)(bs + 3072 + hh * 4);
;                     const float4 e = *(const float4*)(bs + 4096 + hh * 4);
;                     w2[2 * hh] = (f32x2){a.x, a.y}; w2[2 * hh + 1] = (f32x2){a.z, a.w};
;                     kk2[2 * hh] = (f32x2){bq.x, bq.y}; kk2[2 * hh + 1] = (f32x2){bq.z, bq.w};
;                     ka2[2 * hh] = (f32x2){c.x, c.y}; ka2[2 * hh + 1] = (f32x2){c.z, c.w};
;                     kp2[2 * hh] = (f32x2){d.x, d.y}; kp2[2 * hh + 1] = (f32x2){d.z, d.w};
;                     r2[2 * hh] = (f32x2){e.x, e.y}; r2[2 * hh + 1] = (f32x2){e.z, e.w};
;                 }
;                 const float vv = bufp[5120 + s * 32 + wid * 8 + rr];
;                 const f32x2 vv2 = (f32x2){vv, vv};
;                 f32x2 da = S[0] * kk2[0], db = S[1] * kk2[1];
;                 da = S[2] * kk2[2] + da; db = S[3] * kk2[3] + db;
;                 da = da + db;
;                 f32x2 u2[4];
; #pragma unroll
;                 for (int i = 0; i < 4; ++i) u2[i] = S[i] * w2[i] + vv2 * kp2[i];
;                 const float d1 = red8(da.x + da.y);
;                 const f32x2 nd = (f32x2){-d1, -d1};
; #pragma unroll
;                 for (int i = 0; i < 4; ++i) S[i] = nd * ka2[i] + u2[i];
;                 f32x2 ya = S[0] * r2[0], yb = S[1] * r2[1];
;                 ya = S[2] * r2[2] + ya; yb = S[3] * r2[3] + yb;
;                 ya = ya + yb;
;                 const float y = red8(ya.x + ya.y);
;                 yraw[(size_t)(row0 + tile * 16 + s) * 512 + h * 64 + vrow] = y;
;             }
.LBB0_161:
	v_add_u32_e32 v38, s12, v22
	v_add_u32_e32 v39, s12, v36
	s_mov_b32 s12, 0xfffff800
	s_mov_b32 s13, -1
	v_lshl_add_u64 v[30:31], v[28:29], 0, s[12:13]
	ds_read_b128 v[66:69], v38 offset:4096
	ds_read_b128 v[70:73], v38 offset:4112
	ds_read_b128 v[48:51], v38 offset:12288
	ds_read_b128 v[52:55], v38 offset:12304
	ds_read_b128 v[40:43], v38
	ds_read_b128 v[44:47], v38 offset:16
	ds_read_b32 v250, v39
	ds_read_b128 v[56:59], v38 offset:8192
	ds_read_b128 v[60:63], v38 offset:8208
	ds_read_b128 v[74:77], v38 offset:4352
	ds_read_b128 v[78:81], v38 offset:4368
	s_waitcnt lgkmcnt(10)
	v_pk_mul_f32 v[86:87], v[4:5], v[66:67]
	v_pk_mul_f32 v[244:245], v[6:7], v[68:69]
	s_waitcnt lgkmcnt(9)
	v_pk_fma_f32 v[86:87], v[8:9], v[70:71], v[86:87]
	v_pk_fma_f32 v[244:245], v[10:11], v[72:73], v[244:245]
	s_nop 0
	v_pk_add_f32 v[86:87], v[86:87], v[244:245]
	s_nop 0
	v_add_f32_e32 v86, v86, v87
	s_waitcnt lgkmcnt(4)
	v_pk_mul_f32 v[82:83], v[48:49], v[250:251] op_sel_hi:[1,0]
	v_add_f32_dpp v86, v86, v86 quad_perm:[1,0,3,2] row_mask:0xf bank_mask:0xf bound_ctrl:1
	v_pk_mul_f32 v[84:85], v[50:51], v[250:251] op_sel_hi:[1,0]
	v_pk_fma_f32 v[4:5], v[4:5], v[40:41], v[82:83]
	v_add_f32_dpp v86, v86, v86 quad_perm:[2,3,0,1] row_mask:0xf bank_mask:0xf bound_ctrl:1
	v_pk_fma_f32 v[6:7], v[6:7], v[42:43], v[84:85]
	v_pk_mul_f32 v[82:83], v[52:53], v[250:251] op_sel_hi:[1,0]
	v_add_f32_dpp v86, v86, v86 row_half_mirror row_mask:0xf bank_mask:0xf bound_ctrl:1
	v_pk_mul_f32 v[84:85], v[54:55], v[250:251] op_sel_hi:[1,0]
	v_pk_fma_f32 v[8:9], v[8:9], v[44:45], v[82:83]
	v_pk_fma_f32 v[10:11], v[10:11], v[46:47], v[84:85]
	ds_read_b128 v[236:239], v38 offset:16384
	ds_read_b128 v[240:243], v38 offset:16400
	ds_read_b128 v[48:51], v38 offset:12544
	ds_read_b128 v[52:55], v38 offset:12560
	ds_read_b128 v[40:43], v38 offset:256
	ds_read_b128 v[44:47], v38 offset:272
	ds_read_b32 v251, v39 offset:128
	s_waitcnt lgkmcnt(7)
	v_pk_fma_f32 v[4:5], v[56:57], v[86:87], v[4:5] op_sel_hi:[1,0,1] neg_lo:[0,1,0] neg_hi:[0,1,0]
	v_pk_fma_f32 v[6:7], v[58:59], v[86:87], v[6:7] op_sel_hi:[1,0,1] neg_lo:[0,1,0] neg_hi:[0,1,0]
	v_pk_fma_f32 v[8:9], v[60:61], v[86:87], v[8:9] op_sel_hi:[1,0,1] neg_lo:[0,1,0] neg_hi:[0,1,0]
	v_pk_fma_f32 v[10:11], v[62:63], v[86:87], v[10:11] op_sel_hi:[1,0,1] neg_lo:[0,1,0] neg_hi:[0,1,0]
	ds_read_b128 v[56:59], v38 offset:8448
	ds_read_b128 v[60:63], v38 offset:8464
	ds_read_b128 v[66:69], v38 offset:4608
	ds_read_b128 v[70:73], v38 offset:4624
	v_pk_mul_f32 v[86:87], v[4:5], v[74:75]
	v_pk_mul_f32 v[244:245], v[6:7], v[76:77]
	v_pk_fma_f32 v[86:87], v[8:9], v[78:79], v[86:87]
	v_pk_fma_f32 v[244:245], v[10:11], v[80:81], v[244:245]
	s_waitcnt lgkmcnt(10)
	v_pk_mul_f32 v[246:247], v[4:5], v[236:237]
	v_pk_add_f32 v[86:87], v[86:87], v[244:245]
	v_pk_mul_f32 v[248:249], v[6:7], v[238:239]
	v_add_f32_e32 v86, v86, v87
	s_waitcnt lgkmcnt(9)
	v_pk_fma_f32 v[246:247], v[8:9], v[240:241], v[246:247]
	v_pk_fma_f32 v[248:249], v[10:11], v[242:243], v[248:249]
	s_waitcnt lgkmcnt(4)
	v_pk_mul_f32 v[82:83], v[48:49], v[250:251] op_sel:[0,1]
	v_add_f32_dpp v86, v86, v86 quad_perm:[1,0,3,2] row_mask:0xf bank_mask:0xf bound_ctrl:1
	v_pk_mul_f32 v[84:85], v[50:51], v[250:251] op_sel:[0,1]
	v_pk_fma_f32 v[4:5], v[4:5], v[40:41], v[82:83]
	v_add_f32_dpp v86, v86, v86 quad_perm:[2,3,0,1] row_mask:0xf bank_mask:0xf bound_ctrl:1
	v_pk_fma_f32 v[6:7], v[6:7], v[42:43], v[84:85]
	v_pk_mul_f32 v[82:83], v[52:53], v[250:251] op_sel:[0,1]
	v_add_f32_dpp v86, v86, v86 row_half_mirror row_mask:0xf bank_mask:0xf bound_ctrl:1
	v_pk_mul_f32 v[84:85], v[54:55], v[250:251] op_sel:[0,1]
	v_pk_fma_f32 v[8:9], v[8:9], v[44:45], v[82:83]
	v_pk_add_f32 v[246:247], v[246:247], v[248:249]
	v_pk_fma_f32 v[10:11], v[10:11], v[46:47], v[84:85]
	ds_read_b128 v[236:239], v38 offset:16640
	ds_read_b128 v[240:243], v38 offset:16656
	ds_read_b128 v[48:51], v38 offset:12800
	ds_read_b128 v[52:55], v38 offset:12816
	ds_read_b128 v[40:43], v38 offset:512
	ds_read_b128 v[44:47], v38 offset:528
	ds_read_b32 v250, v39 offset:256
	v_add_f32_e32 v246, v246, v247
	s_waitcnt lgkmcnt(7)
	v_pk_fma_f32 v[4:5], v[56:57], v[86:87], v[4:5] op_sel_hi:[1,0,1] neg_lo:[0,1,0] neg_hi:[0,1,0]
	v_pk_fma_f32 v[6:7], v[58:59], v[86:87], v[6:7] op_sel_hi:[1,0,1] neg_lo:[0,1,0] neg_hi:[0,1,0]
	v_add_f32_dpp v246, v246, v246 quad_perm:[1,0,3,2] row_mask:0xf bank_mask:0xf bound_ctrl:1
	v_pk_fma_f32 v[8:9], v[60:61], v[86:87], v[8:9] op_sel_hi:[1,0,1] neg_lo:[0,1,0] neg_hi:[0,1,0]
	v_pk_fma_f32 v[10:11], v[62:63], v[86:87], v[10:11] op_sel_hi:[1,0,1] neg_lo:[0,1,0] neg_hi:[0,1,0]
	v_add_f32_dpp v246, v246, v246 quad_perm:[2,3,0,1] row_mask:0xf bank_mask:0xf bound_ctrl:1
	ds_read_b128 v[56:59], v38 offset:8704
	ds_read_b128 v[60:63], v38 offset:8720
	v_add_f32_dpp v246, v246, v246 row_half_mirror row_mask:0xf bank_mask:0xf bound_ctrl:1
	global_store_dword v[30:31], v246, off offset:-4096
	ds_read_b128 v[74:77], v38 offset:4864
	ds_read_b128 v[78:81], v38 offset:4880
	v_pk_mul_f32 v[86:87], v[4:5], v[66:67]
	v_pk_mul_f32 v[244:245], v[6:7], v[68:69]
	v_pk_fma_f32 v[86:87], v[8:9], v[70:71], v[86:87]
	v_pk_fma_f32 v[244:245], v[10:11], v[72:73], v[244:245]
	s_waitcnt lgkmcnt(10)
	v_pk_mul_f32 v[246:247], v[4:5], v[236:237]
	v_pk_add_f32 v[86:87], v[86:87], v[244:245]
	v_pk_mul_f32 v[248:249], v[6:7], v[238:239]
	v_add_f32_e32 v86, v86, v87
	s_waitcnt lgkmcnt(5)
	v_pk_fma_f32 v[246:247], v[8:9], v[240:241], v[246:247]
	v_pk_fma_f32 v[248:249], v[10:11], v[242:243], v[248:249]
	s_waitcnt lgkmcnt(4)
; __device__ __forceinline__ void rwkv_scan_task(KP p, int l, bool samp, int b, int h, int hb, float* sm) {
;     ...
;         for (int s0 = 0; s0 < nst; s0 += 4) {
; #pragma unroll
;             for (int s4 = 0; s4 < 4; ++s4) {
;                 const int s = s0 + s4;
;                 const float* bs = bufp + s * 64 + ks * 8;
;                 f32x2 w2[4], kk2[4], ka2[4], kp2[4], r2[4];
; #pragma unroll
;                 for (int hh = 0; hh < 2; ++hh) {
;                     const float4 a = *(const float4*)(bs + hh * 4);
;                     const float4 bq = *(const float4*)(bs + 1024 + hh * 4);
;                     const float4 c = *(const float4*)(bs + 2048 + hh * 4);
;                     const float4 d = *(const float4*)(bs + 3072 + hh * 4);
;                     const float4 e = *(const float4*)(bs + 4096 + hh * 4);
;                     w2[2 * hh] = (f32x2){a.x, a.y}; w2[2 * hh + 1] = (f32x2){a.z, a.w};
;                     kk2[2 * hh] = (f32x2){bq.x, bq.y}; kk2[2 * hh + 1] = (f32x2){bq.z, bq.w};
;                     ka2[2 * hh] = (f32x2){c.x, c.y}; ka2[2 * hh + 1] = (f32x2){c.z, c.w};
;                     kp2[2 * hh] = (f32x2){d.x, d.y}; kp2[2 * hh + 1] = (f32x2){d.z, d.w};
;                     r2[2 * hh] = (f32x2){e.x, e.y}; r2[2 * hh + 1] = (f32x2){e.z, e.w};
;                 }
;                 const float vv = bufp[5120 + s * 32 + wid * 8 + rr];
;                 const f32x2 vv2 = (f32x2){vv, vv};
;                 f32x2 da = S[0] * kk2[0], db = S[1] * kk2[1];
;                 da = S[2] * kk2[2] + da; db = S[3] * kk2[3] + db;
;                 da = da + db;
;                 f32x2 u2[4];
; #pragma unroll
;                 for (int i = 0; i < 4; ++i) u2[i] = S[i] * w2[i] + vv2 * kp2[i];
;                 const float d1 = red8(da.x + da.y);
;                 const f32x2 nd = (f32x2){-d1, -d1};
; #pragma unroll
;                 for (int i = 0; i < 4; ++i) S[i] = nd * ka2[i] + u2[i];
;                 f32x2 ya = S[0] * r2[0], yb = S[1] * r2[1];
;                 ya = S[2] * r2[2] + ya; yb = S[3] * r2[3] + yb;
;                 ya = ya + yb;
;                 const float y = red8(ya.x + ya.y);
;                 yraw[(size_t)(row0 + tile * 16 + s) * 512 + h * 64 + vrow] = y;
;             }
	v_pk_mul_f32 v[82:83], v[48:49], v[250:251] op_sel_hi:[1,0]
	v_add_f32_dpp v86, v86, v86 quad_perm:[1,0,3,2] row_mask:0xf bank_mask:0xf bound_ctrl:1
	v_pk_mul_f32 v[84:85], v[50:51], v[250:251] op_sel_hi:[1,0]
	v_pk_fma_f32 v[4:5], v[4:5], v[40:41], v[82:83]
	v_add_f32_dpp v86, v86, v86 quad_perm:[2,3,0,1] row_mask:0xf bank_mask:0xf bound_ctrl:1
	v_pk_fma_f32 v[6:7], v[6:7], v[42:43], v[84:85]
	v_pk_mul_f32 v[82:83], v[52:53], v[250:251] op_sel_hi:[1,0]
	v_add_f32_dpp v86, v86, v86 row_half_mirror row_mask:0xf bank_mask:0xf bound_ctrl:1
	v_pk_mul_f32 v[84:85], v[54:55], v[250:251] op_sel_hi:[1,0]
	v_pk_fma_f32 v[8:9], v[8:9], v[44:45], v[82:83]
	v_pk_add_f32 v[246:247], v[246:247], v[248:249]
	v_pk_fma_f32 v[10:11], v[10:11], v[46:47], v[84:85]
	ds_read_b128 v[236:239], v38 offset:16896
	ds_read_b128 v[240:243], v38 offset:16912
	ds_read_b128 v[48:51], v38 offset:13056
	ds_read_b128 v[52:55], v38 offset:13072
	ds_read_b128 v[40:43], v38 offset:768
	ds_read_b128 v[44:47], v38 offset:784
	ds_read_b32 v251, v39 offset:384
	v_add_f32_e32 v246, v246, v247
	s_waitcnt lgkmcnt(7)
	v_pk_fma_f32 v[4:5], v[56:57], v[86:87], v[4:5] op_sel_hi:[1,0,1] neg_lo:[0,1,0] neg_hi:[0,1,0]
	v_pk_fma_f32 v[6:7], v[58:59], v[86:87], v[6:7] op_sel_hi:[1,0,1] neg_lo:[0,1,0] neg_hi:[0,1,0]
	v_add_f32_dpp v246, v246, v246 quad_perm:[1,0,3,2] row_mask:0xf bank_mask:0xf bound_ctrl:1
	v_pk_fma_f32 v[8:9], v[60:61], v[86:87], v[8:9] op_sel_hi:[1,0,1] neg_lo:[0,1,0] neg_hi:[0,1,0]
	v_pk_fma_f32 v[10:11], v[62:63], v[86:87], v[10:11] op_sel_hi:[1,0,1] neg_lo:[0,1,0] neg_hi:[0,1,0]
	v_add_f32_dpp v246, v246, v246 quad_perm:[2,3,0,1] row_mask:0xf bank_mask:0xf bound_ctrl:1
	ds_read_b128 v[56:59], v38 offset:8960
	ds_read_b128 v[60:63], v38 offset:8976
	v_add_f32_dpp v246, v246, v246 row_half_mirror row_mask:0xf bank_mask:0xf bound_ctrl:1
	global_store_dword v[30:31], v246, off offset:-2048
	ds_read_b128 v[66:69], v38 offset:5120
	ds_read_b128 v[70:73], v38 offset:5136
	v_pk_mul_f32 v[86:87], v[4:5], v[74:75]
	v_pk_mul_f32 v[244:245], v[6:7], v[76:77]
	v_pk_fma_f32 v[86:87], v[8:9], v[78:79], v[86:87]
	v_pk_fma_f32 v[244:245], v[10:11], v[80:81], v[244:245]
	s_waitcnt lgkmcnt(10)
	v_pk_mul_f32 v[246:247], v[4:5], v[236:237]
	v_pk_add_f32 v[86:87], v[86:87], v[244:245]
	v_pk_mul_f32 v[248:249], v[6:7], v[238:239]
	v_add_f32_e32 v86, v86, v87
	s_waitcnt lgkmcnt(5)
	v_pk_fma_f32 v[246:247], v[8:9], v[240:241], v[246:247]
	v_pk_fma_f32 v[248:249], v[10:11], v[242:243], v[248:249]
	s_waitcnt lgkmcnt(4)
	v_pk_mul_f32 v[82:83], v[48:49], v[250:251] op_sel:[0,1]
	v_add_f32_dpp v86, v86, v86 quad_perm:[1,0,3,2] row_mask:0xf bank_mask:0xf bound_ctrl:1
	v_pk_mul_f32 v[84:85], v[50:51], v[250:251] op_sel:[0,1]
	v_pk_fma_f32 v[4:5], v[4:5], v[40:41], v[82:83]
	v_add_f32_dpp v86, v86, v86 quad_perm:[2,3,0,1] row_mask:0xf bank_mask:0xf bound_ctrl:1
	v_pk_fma_f32 v[6:7], v[6:7], v[42:43], v[84:85]
	v_pk_mul_f32 v[82:83], v[52:53], v[250:251] op_sel:[0,1]
	v_add_f32_dpp v86, v86, v86 row_half_mirror row_mask:0xf bank_mask:0xf bound_ctrl:1
	v_pk_mul_f32 v[84:85], v[54:55], v[250:251] op_sel:[0,1]
	v_pk_fma_f32 v[8:9], v[8:9], v[44:45], v[82:83]
	v_pk_add_f32 v[246:247], v[246:247], v[248:249]
	v_pk_fma_f32 v[10:11], v[10:11], v[46:47], v[84:85]
	ds_read_b128 v[236:239], v38 offset:17152
	ds_read_b128 v[240:243], v38 offset:17168
	ds_read_b128 v[48:51], v38 offset:13312
	ds_read_b128 v[52:55], v38 offset:13328
	ds_read_b128 v[40:43], v38 offset:1024
	ds_read_b128 v[44:47], v38 offset:1040
	ds_read_b32 v250, v39 offset:512
	v_add_f32_e32 v246, v246, v247
	s_waitcnt lgkmcnt(7)
	v_pk_fma_f32 v[4:5], v[56:57], v[86:87], v[4:5] op_sel_hi:[1,0,1] neg_lo:[0,1,0] neg_hi:[0,1,0]
	v_pk_fma_f32 v[6:7], v[58:59], v[86:87], v[6:7] op_sel_hi:[1,0,1] neg_lo:[0,1,0] neg_hi:[0,1,0]
	v_add_f32_dpp v246, v246, v246 quad_perm:[1,0,3,2] row_mask:0xf bank_mask:0xf bound_ctrl:1
	v_pk_fma_f32 v[8:9], v[60:61], v[86:87], v[8:9] op_sel_hi:[1,0,1] neg_lo:[0,1,0] neg_hi:[0,1,0]
	v_pk_fma_f32 v[10:11], v[62:63], v[86:87], v[10:11] op_sel_hi:[1,0,1] neg_lo:[0,1,0] neg_hi:[0,1,0]
	v_add_f32_dpp v246, v246, v246 quad_perm:[2,3,0,1] row_mask:0xf bank_mask:0xf bound_ctrl:1
	ds_read_b128 v[56:59], v38 offset:9216
	ds_read_b128 v[60:63], v38 offset:9232
	v_add_f32_dpp v246, v246, v246 row_half_mirror row_mask:0xf bank_mask:0xf bound_ctrl:1
	global_store_dword v[30:31], v246, off
	ds_read_b128 v[74:77], v38 offset:5376
	ds_read_b128 v[78:81], v38 offset:5392
	v_pk_mul_f32 v[86:87], v[4:5], v[66:67]
	v_pk_mul_f32 v[244:245], v[6:7], v[68:69]
	v_pk_fma_f32 v[86:87], v[8:9], v[70:71], v[86:87]
	v_pk_fma_f32 v[244:245], v[10:11], v[72:73], v[244:245]
	s_waitcnt lgkmcnt(10)
	v_pk_mul_f32 v[246:247], v[4:5], v[236:237]
	v_pk_add_f32 v[86:87], v[86:87], v[244:245]
	v_pk_mul_f32 v[248:249], v[6:7], v[238:239]
	v_add_f32_e32 v86, v86, v87
	s_waitcnt lgkmcnt(5)
	v_pk_fma_f32 v[246:247], v[8:9], v[240:241], v[246:247]
	v_pk_fma_f32 v[248:249], v[10:11], v[242:243], v[248:249]
	s_waitcnt lgkmcnt(4)
	v_pk_mul_f32 v[82:83], v[48:49], v[250:251] op_sel_hi:[1,0]
	v_add_f32_dpp v86, v86, v86 quad_perm:[1,0,3,2] row_mask:0xf bank_mask:0xf bound_ctrl:1
	v_pk_mul_f32 v[84:85], v[50:51], v[250:251] op_sel_hi:[1,0]
	v_pk_fma_f32 v[4:5], v[4:5], v[40:41], v[82:83]
	v_add_f32_dpp v86, v86, v86 quad_perm:[2,3,0,1] row_mask:0xf bank_mask:0xf bound_ctrl:1
	v_pk_fma_f32 v[6:7], v[6:7], v[42:43], v[84:85]
	v_pk_mul_f32 v[82:83], v[52:53], v[250:251] op_sel_hi:[1,0]
	v_add_f32_dpp v86, v86, v86 row_half_mirror row_mask:0xf bank_mask:0xf bound_ctrl:1
	v_pk_mul_f32 v[84:85], v[54:55], v[250:251] op_sel_hi:[1,0]
	v_pk_fma_f32 v[8:9], v[8:9], v[44:45], v[82:83]
	v_pk_add_f32 v[246:247], v[246:247], v[248:249]
	v_pk_fma_f32 v[10:11], v[10:11], v[46:47], v[84:85]
	ds_read_b128 v[236:239], v38 offset:17408
	ds_read_b128 v[240:243], v38 offset:17424
	ds_read_b128 v[48:51], v38 offset:13568
	ds_read_b128 v[52:55], v38 offset:13584
	ds_read_b128 v[40:43], v38 offset:1280
	ds_read_b128 v[44:47], v38 offset:1296
	ds_read_b32 v251, v39 offset:640
	v_add_f32_e32 v246, v246, v247
	s_waitcnt lgkmcnt(7)
; __device__ __forceinline__ void rwkv_scan_task(KP p, int l, bool samp, int b, int h, int hb, float* sm) {
;     ...
;         for (int s0 = 0; s0 < nst; s0 += 4) {
; #pragma unroll
;             for (int s4 = 0; s4 < 4; ++s4) {
;                 const int s = s0 + s4;
;                 const float* bs = bufp + s * 64 + ks * 8;
;                 f32x2 w2[4], kk2[4], ka2[4], kp2[4], r2[4];
; #pragma unroll
;                 for (int hh = 0; hh < 2; ++hh) {
;                     const float4 a = *(const float4*)(bs + hh * 4);
;                     const float4 bq = *(const float4*)(bs + 1024 + hh * 4);
;                     const float4 c = *(const float4*)(bs + 2048 + hh * 4);
;                     const float4 d = *(const float4*)(bs + 3072 + hh * 4);
;                     const float4 e = *(const float4*)(bs + 4096 + hh * 4);
;                     w2[2 * hh] = (f32x2){a.x, a.y}; w2[2 * hh + 1] = (f32x2){a.z, a.w};
;                     kk2[2 * hh] = (f32x2){bq.x, bq.y}; kk2[2 * hh + 1] = (f32x2){bq.z, bq.w};
;                     ka2[2 * hh] = (f32x2){c.x, c.y}; ka2[2 * hh + 1] = (f32x2){c.z, c.w};
;                     kp2[2 * hh] = (f32x2){d.x, d.y}; kp2[2 * hh + 1] = (f32x2){d.z, d.w};
;                     r2[2 * hh] = (f32x2){e.x, e.y}; r2[2 * hh + 1] = (f32x2){e.z, e.w};
;                 }
;                 const float vv = bufp[5120 + s * 32 + wid * 8 + rr];
;                 const f32x2 vv2 = (f32x2){vv, vv};
;                 f32x2 da = S[0] * kk2[0], db = S[1] * kk2[1];
;                 da = S[2] * kk2[2] + da; db = S[3] * kk2[3] + db;
;                 da = da + db;
;                 f32x2 u2[4];
; #pragma unroll
;                 for (int i = 0; i < 4; ++i) u2[i] = S[i] * w2[i] + vv2 * kp2[i];
;                 const float d1 = red8(da.x + da.y);
;                 const f32x2 nd = (f32x2){-d1, -d1};
; #pragma unroll
;                 for (int i = 0; i < 4; ++i) S[i] = nd * ka2[i] + u2[i];
;                 f32x2 ya = S[0] * r2[0], yb = S[1] * r2[1];
;                 ya = S[2] * r2[2] + ya; yb = S[3] * r2[3] + yb;
;                 ya = ya + yb;
;                 const float y = red8(ya.x + ya.y);
;                 yraw[(size_t)(row0 + tile * 16 + s) * 512 + h * 64 + vrow] = y;
;             }
	v_pk_fma_f32 v[4:5], v[56:57], v[86:87], v[4:5] op_sel_hi:[1,0,1] neg_lo:[0,1,0] neg_hi:[0,1,0]
	v_pk_fma_f32 v[6:7], v[58:59], v[86:87], v[6:7] op_sel_hi:[1,0,1] neg_lo:[0,1,0] neg_hi:[0,1,0]
	v_add_f32_dpp v246, v246, v246 quad_perm:[1,0,3,2] row_mask:0xf bank_mask:0xf bound_ctrl:1
	v_pk_fma_f32 v[8:9], v[60:61], v[86:87], v[8:9] op_sel_hi:[1,0,1] neg_lo:[0,1,0] neg_hi:[0,1,0]
	v_pk_fma_f32 v[10:11], v[62:63], v[86:87], v[10:11] op_sel_hi:[1,0,1] neg_lo:[0,1,0] neg_hi:[0,1,0]
	v_add_f32_dpp v246, v246, v246 quad_perm:[2,3,0,1] row_mask:0xf bank_mask:0xf bound_ctrl:1
	ds_read_b128 v[56:59], v38 offset:9472
	ds_read_b128 v[60:63], v38 offset:9488
	v_add_f32_dpp v246, v246, v246 row_half_mirror row_mask:0xf bank_mask:0xf bound_ctrl:1
	global_store_dword v[30:31], v246, off offset:2048
	v_lshl_add_u64 v[30:31], v[30:31], 0, s[20:21]
	ds_read_b128 v[66:69], v38 offset:5632
	ds_read_b128 v[70:73], v38 offset:5648
	v_pk_mul_f32 v[86:87], v[4:5], v[74:75]
	v_pk_mul_f32 v[244:245], v[6:7], v[76:77]
	v_pk_fma_f32 v[86:87], v[8:9], v[78:79], v[86:87]
	v_pk_fma_f32 v[244:245], v[10:11], v[80:81], v[244:245]
	s_waitcnt lgkmcnt(9)
	v_pk_mul_f32 v[246:247], v[4:5], v[236:237]
	v_pk_add_f32 v[86:87], v[86:87], v[244:245]
	v_pk_mul_f32 v[248:249], v[6:7], v[238:239]
	v_add_f32_e32 v86, v86, v87
	v_pk_fma_f32 v[246:247], v[8:9], v[240:241], v[246:247]
	v_pk_fma_f32 v[248:249], v[10:11], v[242:243], v[248:249]
	s_waitcnt lgkmcnt(4)
	v_pk_mul_f32 v[82:83], v[48:49], v[250:251] op_sel:[0,1]
	v_add_f32_dpp v86, v86, v86 quad_perm:[1,0,3,2] row_mask:0xf bank_mask:0xf bound_ctrl:1
	v_pk_mul_f32 v[84:85], v[50:51], v[250:251] op_sel:[0,1]
	v_pk_fma_f32 v[4:5], v[4:5], v[40:41], v[82:83]
	v_add_f32_dpp v86, v86, v86 quad_perm:[2,3,0,1] row_mask:0xf bank_mask:0xf bound_ctrl:1
	v_pk_fma_f32 v[6:7], v[6:7], v[42:43], v[84:85]
	v_pk_mul_f32 v[82:83], v[52:53], v[250:251] op_sel:[0,1]
	v_add_f32_dpp v86, v86, v86 row_half_mirror row_mask:0xf bank_mask:0xf bound_ctrl:1
	v_pk_mul_f32 v[84:85], v[54:55], v[250:251] op_sel:[0,1]
	v_pk_fma_f32 v[8:9], v[8:9], v[44:45], v[82:83]
	v_pk_add_f32 v[246:247], v[246:247], v[248:249]
	v_pk_fma_f32 v[10:11], v[10:11], v[46:47], v[84:85]
	ds_read_b128 v[236:239], v38 offset:17664
	ds_read_b128 v[240:243], v38 offset:17680
	ds_read_b128 v[48:51], v38 offset:13824
	ds_read_b128 v[52:55], v38 offset:13840
	ds_read_b128 v[40:43], v38 offset:1536
	ds_read_b128 v[44:47], v38 offset:1552
	ds_read_b32 v250, v39 offset:768
	v_add_f32_e32 v246, v246, v247
	s_waitcnt lgkmcnt(7)
	v_pk_fma_f32 v[4:5], v[56:57], v[86:87], v[4:5] op_sel_hi:[1,0,1] neg_lo:[0,1,0] neg_hi:[0,1,0]
	v_pk_fma_f32 v[6:7], v[58:59], v[86:87], v[6:7] op_sel_hi:[1,0,1] neg_lo:[0,1,0] neg_hi:[0,1,0]
	v_add_f32_dpp v246, v246, v246 quad_perm:[1,0,3,2] row_mask:0xf bank_mask:0xf bound_ctrl:1
	v_pk_fma_f32 v[8:9], v[60:61], v[86:87], v[8:9] op_sel_hi:[1,0,1] neg_lo:[0,1,0] neg_hi:[0,1,0]
	v_pk_fma_f32 v[10:11], v[62:63], v[86:87], v[10:11] op_sel_hi:[1,0,1] neg_lo:[0,1,0] neg_hi:[0,1,0]
	v_add_f32_dpp v246, v246, v246 quad_perm:[2,3,0,1] row_mask:0xf bank_mask:0xf bound_ctrl:1
	ds_read_b128 v[56:59], v38 offset:9728
	ds_read_b128 v[60:63], v38 offset:9744
	v_add_f32_dpp v246, v246, v246 row_half_mirror row_mask:0xf bank_mask:0xf bound_ctrl:1
	global_store_dword v[30:31], v246, off offset:-4096
	ds_read_b128 v[74:77], v38 offset:5888
	ds_read_b128 v[78:81], v38 offset:5904
	v_pk_mul_f32 v[86:87], v[4:5], v[66:67]
	v_pk_mul_f32 v[244:245], v[6:7], v[68:69]
	v_pk_fma_f32 v[86:87], v[8:9], v[70:71], v[86:87]
	v_pk_fma_f32 v[244:245], v[10:11], v[72:73], v[244:245]
	s_waitcnt lgkmcnt(10)
	v_pk_mul_f32 v[246:247], v[4:5], v[236:237]
	v_pk_add_f32 v[86:87], v[86:87], v[244:245]
	v_pk_mul_f32 v[248:249], v[6:7], v[238:239]
	v_add_f32_e32 v86, v86, v87
	s_waitcnt lgkmcnt(5)
	v_pk_fma_f32 v[246:247], v[8:9], v[240:241], v[246:247]
	v_pk_fma_f32 v[248:249], v[10:11], v[242:243], v[248:249]
	s_waitcnt lgkmcnt(4)
	v_pk_mul_f32 v[82:83], v[48:49], v[250:251] op_sel_hi:[1,0]
	v_add_f32_dpp v86, v86, v86 quad_perm:[1,0,3,2] row_mask:0xf bank_mask:0xf bound_ctrl:1
	v_pk_mul_f32 v[84:85], v[50:51], v[250:251] op_sel_hi:[1,0]
	v_pk_fma_f32 v[4:5], v[4:5], v[40:41], v[82:83]
	v_add_f32_dpp v86, v86, v86 quad_perm:[2,3,0,1] row_mask:0xf bank_mask:0xf bound_ctrl:1
	v_pk_fma_f32 v[6:7], v[6:7], v[42:43], v[84:85]
	v_pk_mul_f32 v[82:83], v[52:53], v[250:251] op_sel_hi:[1,0]
	v_add_f32_dpp v86, v86, v86 row_half_mirror row_mask:0xf bank_mask:0xf bound_ctrl:1
	v_pk_mul_f32 v[84:85], v[54:55], v[250:251] op_sel_hi:[1,0]
	v_pk_fma_f32 v[8:9], v[8:9], v[44:45], v[82:83]
	v_pk_add_f32 v[246:247], v[246:247], v[248:249]
	v_pk_fma_f32 v[10:11], v[10:11], v[46:47], v[84:85]
	ds_read_b128 v[236:239], v38 offset:17920
	ds_read_b128 v[240:243], v38 offset:17936
	ds_read_b128 v[48:51], v38 offset:14080
	ds_read_b128 v[52:55], v38 offset:14096
	ds_read_b128 v[40:43], v38 offset:1792
	ds_read_b128 v[44:47], v38 offset:1808
	ds_read_b32 v251, v39 offset:896
	v_add_f32_e32 v246, v246, v247
	s_waitcnt lgkmcnt(7)
	v_pk_fma_f32 v[4:5], v[56:57], v[86:87], v[4:5] op_sel_hi:[1,0,1] neg_lo:[0,1,0] neg_hi:[0,1,0]
	v_pk_fma_f32 v[6:7], v[58:59], v[86:87], v[6:7] op_sel_hi:[1,0,1] neg_lo:[0,1,0] neg_hi:[0,1,0]
	v_add_f32_dpp v246, v246, v246 quad_perm:[1,0,3,2] row_mask:0xf bank_mask:0xf bound_ctrl:1
	v_pk_fma_f32 v[8:9], v[60:61], v[86:87], v[8:9] op_sel_hi:[1,0,1] neg_lo:[0,1,0] neg_hi:[0,1,0]
	v_pk_fma_f32 v[10:11], v[62:63], v[86:87], v[10:11] op_sel_hi:[1,0,1] neg_lo:[0,1,0] neg_hi:[0,1,0]
	v_add_f32_dpp v246, v246, v246 quad_perm:[2,3,0,1] row_mask:0xf bank_mask:0xf bound_ctrl:1
	ds_read_b128 v[56:59], v38 offset:9984
	ds_read_b128 v[60:63], v38 offset:10000
	v_add_f32_dpp v246, v246, v246 row_half_mirror row_mask:0xf bank_mask:0xf bound_ctrl:1
	global_store_dword v[30:31], v246, off offset:-2048
	ds_read_b128 v[66:69], v38 offset:6144
	ds_read_b128 v[70:73], v38 offset:6160
	v_pk_mul_f32 v[86:87], v[4:5], v[74:75]
	v_pk_mul_f32 v[244:245], v[6:7], v[76:77]
	v_pk_fma_f32 v[86:87], v[8:9], v[78:79], v[86:87]
	v_pk_fma_f32 v[244:245], v[10:11], v[80:81], v[244:245]
	s_waitcnt lgkmcnt(10)
; __device__ __forceinline__ void rwkv_scan_task(KP p, int l, bool samp, int b, int h, int hb, float* sm) {
;     ...
;         for (int s0 = 0; s0 < nst; s0 += 4) {
; #pragma unroll
;             for (int s4 = 0; s4 < 4; ++s4) {
;                 const int s = s0 + s4;
;                 const float* bs = bufp + s * 64 + ks * 8;
;                 f32x2 w2[4], kk2[4], ka2[4], kp2[4], r2[4];
; #pragma unroll
;                 for (int hh = 0; hh < 2; ++hh) {
;                     const float4 a = *(const float4*)(bs + hh * 4);
;                     const float4 bq = *(const float4*)(bs + 1024 + hh * 4);
;                     const float4 c = *(const float4*)(bs + 2048 + hh * 4);
;                     const float4 d = *(const float4*)(bs + 3072 + hh * 4);
;                     const float4 e = *(const float4*)(bs + 4096 + hh * 4);
;                     w2[2 * hh] = (f32x2){a.x, a.y}; w2[2 * hh + 1] = (f32x2){a.z, a.w};
;                     kk2[2 * hh] = (f32x2){bq.x, bq.y}; kk2[2 * hh + 1] = (f32x2){bq.z, bq.w};
;                     ka2[2 * hh] = (f32x2){c.x, c.y}; ka2[2 * hh + 1] = (f32x2){c.z, c.w};
;                     kp2[2 * hh] = (f32x2){d.x, d.y}; kp2[2 * hh + 1] = (f32x2){d.z, d.w};
;                     r2[2 * hh] = (f32x2){e.x, e.y}; r2[2 * hh + 1] = (f32x2){e.z, e.w};
;                 }
;                 const float vv = bufp[5120 + s * 32 + wid * 8 + rr];
;                 const f32x2 vv2 = (f32x2){vv, vv};
;                 f32x2 da = S[0] * kk2[0], db = S[1] * kk2[1];
;                 da = S[2] * kk2[2] + da; db = S[3] * kk2[3] + db;
;                 da = da + db;
;                 f32x2 u2[4];
; #pragma unroll
;                 for (int i = 0; i < 4; ++i) u2[i] = S[i] * w2[i] + vv2 * kp2[i];
;                 const float d1 = red8(da.x + da.y);
;                 const f32x2 nd = (f32x2){-d1, -d1};
; #pragma unroll
;                 for (int i = 0; i < 4; ++i) S[i] = nd * ka2[i] + u2[i];
;                 f32x2 ya = S[0] * r2[0], yb = S[1] * r2[1];
;                 ya = S[2] * r2[2] + ya; yb = S[3] * r2[3] + yb;
;                 ya = ya + yb;
;                 const float y = red8(ya.x + ya.y);
;                 yraw[(size_t)(row0 + tile * 16 + s) * 512 + h * 64 + vrow] = y;
;             }
	v_pk_mul_f32 v[246:247], v[4:5], v[236:237]
	v_pk_add_f32 v[86:87], v[86:87], v[244:245]
	v_pk_mul_f32 v[248:249], v[6:7], v[238:239]
	v_add_f32_e32 v86, v86, v87
	s_waitcnt lgkmcnt(5)
	v_pk_fma_f32 v[246:247], v[8:9], v[240:241], v[246:247]
	v_pk_fma_f32 v[248:249], v[10:11], v[242:243], v[248:249]
	s_waitcnt lgkmcnt(4)
	v_pk_mul_f32 v[82:83], v[48:49], v[250:251] op_sel:[0,1]
	v_add_f32_dpp v86, v86, v86 quad_perm:[1,0,3,2] row_mask:0xf bank_mask:0xf bound_ctrl:1
	v_pk_mul_f32 v[84:85], v[50:51], v[250:251] op_sel:[0,1]
	v_pk_fma_f32 v[4:5], v[4:5], v[40:41], v[82:83]
	v_add_f32_dpp v86, v86, v86 quad_perm:[2,3,0,1] row_mask:0xf bank_mask:0xf bound_ctrl:1
	v_pk_fma_f32 v[6:7], v[6:7], v[42:43], v[84:85]
	v_pk_mul_f32 v[82:83], v[52:53], v[250:251] op_sel:[0,1]
	v_add_f32_dpp v86, v86, v86 row_half_mirror row_mask:0xf bank_mask:0xf bound_ctrl:1
	v_pk_mul_f32 v[84:85], v[54:55], v[250:251] op_sel:[0,1]
	v_pk_fma_f32 v[8:9], v[8:9], v[44:45], v[82:83]
	v_pk_add_f32 v[246:247], v[246:247], v[248:249]
	v_pk_fma_f32 v[10:11], v[10:11], v[46:47], v[84:85]
	ds_read_b128 v[236:239], v38 offset:18176
	ds_read_b128 v[240:243], v38 offset:18192
	ds_read_b128 v[48:51], v38 offset:14336
	ds_read_b128 v[52:55], v38 offset:14352
	ds_read_b128 v[40:43], v38 offset:2048
	ds_read_b128 v[44:47], v38 offset:2064
	ds_read_b32 v250, v39 offset:1024
	v_add_f32_e32 v246, v246, v247
	s_waitcnt lgkmcnt(7)
	v_pk_fma_f32 v[4:5], v[56:57], v[86:87], v[4:5] op_sel_hi:[1,0,1] neg_lo:[0,1,0] neg_hi:[0,1,0]
	v_pk_fma_f32 v[6:7], v[58:59], v[86:87], v[6:7] op_sel_hi:[1,0,1] neg_lo:[0,1,0] neg_hi:[0,1,0]
	v_add_f32_dpp v246, v246, v246 quad_perm:[1,0,3,2] row_mask:0xf bank_mask:0xf bound_ctrl:1
	v_pk_fma_f32 v[8:9], v[60:61], v[86:87], v[8:9] op_sel_hi:[1,0,1] neg_lo:[0,1,0] neg_hi:[0,1,0]
	v_pk_fma_f32 v[10:11], v[62:63], v[86:87], v[10:11] op_sel_hi:[1,0,1] neg_lo:[0,1,0] neg_hi:[0,1,0]
	v_add_f32_dpp v246, v246, v246 quad_perm:[2,3,0,1] row_mask:0xf bank_mask:0xf bound_ctrl:1
	ds_read_b128 v[56:59], v38 offset:10240
	ds_read_b128 v[60:63], v38 offset:10256
	v_add_f32_dpp v246, v246, v246 row_half_mirror row_mask:0xf bank_mask:0xf bound_ctrl:1
	global_store_dword v[30:31], v246, off
	ds_read_b128 v[74:77], v38 offset:6400
	ds_read_b128 v[78:81], v38 offset:6416
	v_pk_mul_f32 v[86:87], v[4:5], v[66:67]
	v_pk_mul_f32 v[244:245], v[6:7], v[68:69]
	v_pk_fma_f32 v[86:87], v[8:9], v[70:71], v[86:87]
	v_pk_fma_f32 v[244:245], v[10:11], v[72:73], v[244:245]
	s_waitcnt lgkmcnt(10)
	v_pk_mul_f32 v[246:247], v[4:5], v[236:237]
	v_pk_add_f32 v[86:87], v[86:87], v[244:245]
	v_pk_mul_f32 v[248:249], v[6:7], v[238:239]
	v_add_f32_e32 v86, v86, v87
	s_waitcnt lgkmcnt(5)
	v_pk_fma_f32 v[246:247], v[8:9], v[240:241], v[246:247]
	v_pk_fma_f32 v[248:249], v[10:11], v[242:243], v[248:249]
	s_waitcnt lgkmcnt(4)
	v_pk_mul_f32 v[82:83], v[48:49], v[250:251] op_sel_hi:[1,0]
	v_add_f32_dpp v86, v86, v86 quad_perm:[1,0,3,2] row_mask:0xf bank_mask:0xf bound_ctrl:1
	v_pk_mul_f32 v[84:85], v[50:51], v[250:251] op_sel_hi:[1,0]
	v_pk_fma_f32 v[4:5], v[4:5], v[40:41], v[82:83]
	v_add_f32_dpp v86, v86, v86 quad_perm:[2,3,0,1] row_mask:0xf bank_mask:0xf bound_ctrl:1
	v_pk_fma_f32 v[6:7], v[6:7], v[42:43], v[84:85]
	v_pk_mul_f32 v[82:83], v[52:53], v[250:251] op_sel_hi:[1,0]
	v_add_f32_dpp v86, v86, v86 row_half_mirror row_mask:0xf bank_mask:0xf bound_ctrl:1
	v_pk_mul_f32 v[84:85], v[54:55], v[250:251] op_sel_hi:[1,0]
	v_pk_fma_f32 v[8:9], v[8:9], v[44:45], v[82:83]
	v_pk_add_f32 v[246:247], v[246:247], v[248:249]
	v_pk_fma_f32 v[10:11], v[10:11], v[46:47], v[84:85]
	ds_read_b128 v[236:239], v38 offset:18432
	ds_read_b128 v[240:243], v38 offset:18448
	ds_read_b128 v[48:51], v38 offset:14592
	ds_read_b128 v[52:55], v38 offset:14608
	ds_read_b128 v[40:43], v38 offset:2304
	ds_read_b128 v[44:47], v38 offset:2320
	ds_read_b32 v251, v39 offset:1152
	v_add_f32_e32 v246, v246, v247
	s_waitcnt lgkmcnt(7)
	v_pk_fma_f32 v[4:5], v[56:57], v[86:87], v[4:5] op_sel_hi:[1,0,1] neg_lo:[0,1,0] neg_hi:[0,1,0]
	v_pk_fma_f32 v[6:7], v[58:59], v[86:87], v[6:7] op_sel_hi:[1,0,1] neg_lo:[0,1,0] neg_hi:[0,1,0]
	v_add_f32_dpp v246, v246, v246 quad_perm:[1,0,3,2] row_mask:0xf bank_mask:0xf bound_ctrl:1
	v_pk_fma_f32 v[8:9], v[60:61], v[86:87], v[8:9] op_sel_hi:[1,0,1] neg_lo:[0,1,0] neg_hi:[0,1,0]
	v_pk_fma_f32 v[10:11], v[62:63], v[86:87], v[10:11] op_sel_hi:[1,0,1] neg_lo:[0,1,0] neg_hi:[0,1,0]
	v_add_f32_dpp v246, v246, v246 quad_perm:[2,3,0,1] row_mask:0xf bank_mask:0xf bound_ctrl:1
	ds_read_b128 v[56:59], v38 offset:10496
	ds_read_b128 v[60:63], v38 offset:10512
	v_add_f32_dpp v246, v246, v246 row_half_mirror row_mask:0xf bank_mask:0xf bound_ctrl:1
	global_store_dword v[30:31], v246, off offset:2048
	v_lshl_add_u64 v[30:31], v[30:31], 0, s[20:21]
	ds_read_b128 v[66:69], v38 offset:6656
	ds_read_b128 v[70:73], v38 offset:6672
	v_pk_mul_f32 v[86:87], v[4:5], v[74:75]
	v_pk_mul_f32 v[244:245], v[6:7], v[76:77]
	v_pk_fma_f32 v[86:87], v[8:9], v[78:79], v[86:87]
	v_pk_fma_f32 v[244:245], v[10:11], v[80:81], v[244:245]
	s_waitcnt lgkmcnt(9)
	v_pk_mul_f32 v[246:247], v[4:5], v[236:237]
	v_pk_add_f32 v[86:87], v[86:87], v[244:245]
	v_pk_mul_f32 v[248:249], v[6:7], v[238:239]
	v_add_f32_e32 v86, v86, v87
	v_pk_fma_f32 v[246:247], v[8:9], v[240:241], v[246:247]
	v_pk_fma_f32 v[248:249], v[10:11], v[242:243], v[248:249]
	s_waitcnt lgkmcnt(4)
; __device__ __forceinline__ void rwkv_scan_task(KP p, int l, bool samp, int b, int h, int hb, float* sm) {
;     ...
;         for (int s0 = 0; s0 < nst; s0 += 4) {
; #pragma unroll
;             for (int s4 = 0; s4 < 4; ++s4) {
;                 const int s = s0 + s4;
;                 const float* bs = bufp + s * 64 + ks * 8;
;                 f32x2 w2[4], kk2[4], ka2[4], kp2[4], r2[4];
; #pragma unroll
;                 for (int hh = 0; hh < 2; ++hh) {
;                     const float4 a = *(const float4*)(bs + hh * 4);
;                     const float4 bq = *(const float4*)(bs + 1024 + hh * 4);
;                     const float4 c = *(const float4*)(bs + 2048 + hh * 4);
;                     const float4 d = *(const float4*)(bs + 3072 + hh * 4);
;                     const float4 e = *(const float4*)(bs + 4096 + hh * 4);
;                     w2[2 * hh] = (f32x2){a.x, a.y}; w2[2 * hh + 1] = (f32x2){a.z, a.w};
;                     kk2[2 * hh] = (f32x2){bq.x, bq.y}; kk2[2 * hh + 1] = (f32x2){bq.z, bq.w};
;                     ka2[2 * hh] = (f32x2){c.x, c.y}; ka2[2 * hh + 1] = (f32x2){c.z, c.w};
;                     kp2[2 * hh] = (f32x2){d.x, d.y}; kp2[2 * hh + 1] = (f32x2){d.z, d.w};
;                     r2[2 * hh] = (f32x2){e.x, e.y}; r2[2 * hh + 1] = (f32x2){e.z, e.w};
;                 }
;                 const float vv = bufp[5120 + s * 32 + wid * 8 + rr];
;                 const f32x2 vv2 = (f32x2){vv, vv};
;                 f32x2 da = S[0] * kk2[0], db = S[1] * kk2[1];
;                 da = S[2] * kk2[2] + da; db = S[3] * kk2[3] + db;
;                 da = da + db;
;                 f32x2 u2[4];
; #pragma unroll
;                 for (int i = 0; i < 4; ++i) u2[i] = S[i] * w2[i] + vv2 * kp2[i];
;                 const float d1 = red8(da.x + da.y);
;                 const f32x2 nd = (f32x2){-d1, -d1};
; #pragma unroll
;                 for (int i = 0; i < 4; ++i) S[i] = nd * ka2[i] + u2[i];
;                 f32x2 ya = S[0] * r2[0], yb = S[1] * r2[1];
;                 ya = S[2] * r2[2] + ya; yb = S[3] * r2[3] + yb;
;                 ya = ya + yb;
;                 const float y = red8(ya.x + ya.y);
;                 yraw[(size_t)(row0 + tile * 16 + s) * 512 + h * 64 + vrow] = y;
;             }
	v_pk_mul_f32 v[82:83], v[48:49], v[250:251] op_sel:[0,1]
	v_add_f32_dpp v86, v86, v86 quad_perm:[1,0,3,2] row_mask:0xf bank_mask:0xf bound_ctrl:1
	v_pk_mul_f32 v[84:85], v[50:51], v[250:251] op_sel:[0,1]
	v_pk_fma_f32 v[4:5], v[4:5], v[40:41], v[82:83]
	v_add_f32_dpp v86, v86, v86 quad_perm:[2,3,0,1] row_mask:0xf bank_mask:0xf bound_ctrl:1
	v_pk_fma_f32 v[6:7], v[6:7], v[42:43], v[84:85]
	v_pk_mul_f32 v[82:83], v[52:53], v[250:251] op_sel:[0,1]
	v_add_f32_dpp v86, v86, v86 row_half_mirror row_mask:0xf bank_mask:0xf bound_ctrl:1
	v_pk_mul_f32 v[84:85], v[54:55], v[250:251] op_sel:[0,1]
	v_pk_fma_f32 v[8:9], v[8:9], v[44:45], v[82:83]
	v_pk_add_f32 v[246:247], v[246:247], v[248:249]
	v_pk_fma_f32 v[10:11], v[10:11], v[46:47], v[84:85]
	ds_read_b128 v[236:239], v38 offset:18688
	ds_read_b128 v[240:243], v38 offset:18704
	ds_read_b128 v[48:51], v38 offset:14848
	ds_read_b128 v[52:55], v38 offset:14864
	ds_read_b128 v[40:43], v38 offset:2560
	ds_read_b128 v[44:47], v38 offset:2576
	ds_read_b32 v250, v39 offset:1280
	v_add_f32_e32 v246, v246, v247
	s_waitcnt lgkmcnt(7)
	v_pk_fma_f32 v[4:5], v[56:57], v[86:87], v[4:5] op_sel_hi:[1,0,1] neg_lo:[0,1,0] neg_hi:[0,1,0]
	v_pk_fma_f32 v[6:7], v[58:59], v[86:87], v[6:7] op_sel_hi:[1,0,1] neg_lo:[0,1,0] neg_hi:[0,1,0]
	v_add_f32_dpp v246, v246, v246 quad_perm:[1,0,3,2] row_mask:0xf bank_mask:0xf bound_ctrl:1
	v_pk_fma_f32 v[8:9], v[60:61], v[86:87], v[8:9] op_sel_hi:[1,0,1] neg_lo:[0,1,0] neg_hi:[0,1,0]
	v_pk_fma_f32 v[10:11], v[62:63], v[86:87], v[10:11] op_sel_hi:[1,0,1] neg_lo:[0,1,0] neg_hi:[0,1,0]
	v_add_f32_dpp v246, v246, v246 quad_perm:[2,3,0,1] row_mask:0xf bank_mask:0xf bound_ctrl:1
	ds_read_b128 v[56:59], v38 offset:10752
	ds_read_b128 v[60:63], v38 offset:10768
	v_add_f32_dpp v246, v246, v246 row_half_mirror row_mask:0xf bank_mask:0xf bound_ctrl:1
	global_store_dword v[30:31], v246, off offset:-4096
	ds_read_b128 v[74:77], v38 offset:6912
	ds_read_b128 v[78:81], v38 offset:6928
	v_pk_mul_f32 v[86:87], v[4:5], v[66:67]
	v_pk_mul_f32 v[244:245], v[6:7], v[68:69]
	v_pk_fma_f32 v[86:87], v[8:9], v[70:71], v[86:87]
	v_pk_fma_f32 v[244:245], v[10:11], v[72:73], v[244:245]
	s_waitcnt lgkmcnt(10)
	v_pk_mul_f32 v[246:247], v[4:5], v[236:237]
	v_pk_add_f32 v[86:87], v[86:87], v[244:245]
	v_pk_mul_f32 v[248:249], v[6:7], v[238:239]
	v_add_f32_e32 v86, v86, v87
	s_waitcnt lgkmcnt(5)
	v_pk_fma_f32 v[246:247], v[8:9], v[240:241], v[246:247]
	v_pk_fma_f32 v[248:249], v[10:11], v[242:243], v[248:249]
	s_waitcnt lgkmcnt(4)
	v_pk_mul_f32 v[82:83], v[48:49], v[250:251] op_sel_hi:[1,0]
	v_add_f32_dpp v86, v86, v86 quad_perm:[1,0,3,2] row_mask:0xf bank_mask:0xf bound_ctrl:1
	v_pk_mul_f32 v[84:85], v[50:51], v[250:251] op_sel_hi:[1,0]
	v_pk_fma_f32 v[4:5], v[4:5], v[40:41], v[82:83]
	v_add_f32_dpp v86, v86, v86 quad_perm:[2,3,0,1] row_mask:0xf bank_mask:0xf bound_ctrl:1
	v_pk_fma_f32 v[6:7], v[6:7], v[42:43], v[84:85]
	v_pk_mul_f32 v[82:83], v[52:53], v[250:251] op_sel_hi:[1,0]
	v_add_f32_dpp v86, v86, v86 row_half_mirror row_mask:0xf bank_mask:0xf bound_ctrl:1
	v_pk_mul_f32 v[84:85], v[54:55], v[250:251] op_sel_hi:[1,0]
	v_pk_fma_f32 v[8:9], v[8:9], v[44:45], v[82:83]
	v_pk_add_f32 v[246:247], v[246:247], v[248:249]
	v_pk_fma_f32 v[10:11], v[10:11], v[46:47], v[84:85]
	ds_read_b128 v[236:239], v38 offset:18944
	ds_read_b128 v[240:243], v38 offset:18960
	ds_read_b128 v[48:51], v38 offset:15104
	ds_read_b128 v[52:55], v38 offset:15120
	ds_read_b128 v[40:43], v38 offset:2816
	ds_read_b128 v[44:47], v38 offset:2832
	ds_read_b32 v251, v39 offset:1408
	v_add_f32_e32 v246, v246, v247
	s_waitcnt lgkmcnt(7)
	v_pk_fma_f32 v[4:5], v[56:57], v[86:87], v[4:5] op_sel_hi:[1,0,1] neg_lo:[0,1,0] neg_hi:[0,1,0]
	v_pk_fma_f32 v[6:7], v[58:59], v[86:87], v[6:7] op_sel_hi:[1,0,1] neg_lo:[0,1,0] neg_hi:[0,1,0]
	v_add_f32_dpp v246, v246, v246 quad_perm:[1,0,3,2] row_mask:0xf bank_mask:0xf bound_ctrl:1
	v_pk_fma_f32 v[8:9], v[60:61], v[86:87], v[8:9] op_sel_hi:[1,0,1] neg_lo:[0,1,0] neg_hi:[0,1,0]
	v_pk_fma_f32 v[10:11], v[62:63], v[86:87], v[10:11] op_sel_hi:[1,0,1] neg_lo:[0,1,0] neg_hi:[0,1,0]
	v_add_f32_dpp v246, v246, v246 quad_perm:[2,3,0,1] row_mask:0xf bank_mask:0xf bound_ctrl:1
	ds_read_b128 v[56:59], v38 offset:11008
	ds_read_b128 v[60:63], v38 offset:11024
	v_add_f32_dpp v246, v246, v246 row_half_mirror row_mask:0xf bank_mask:0xf bound_ctrl:1
	global_store_dword v[30:31], v246, off offset:-2048
	ds_read_b128 v[66:69], v38 offset:7168
	ds_read_b128 v[70:73], v38 offset:7184
	v_pk_mul_f32 v[86:87], v[4:5], v[74:75]
	v_pk_mul_f32 v[244:245], v[6:7], v[76:77]
	v_pk_fma_f32 v[86:87], v[8:9], v[78:79], v[86:87]
	v_pk_fma_f32 v[244:245], v[10:11], v[80:81], v[244:245]
	s_waitcnt lgkmcnt(10)
	v_pk_mul_f32 v[246:247], v[4:5], v[236:237]
	v_pk_add_f32 v[86:87], v[86:87], v[244:245]
	v_pk_mul_f32 v[248:249], v[6:7], v[238:239]
	v_add_f32_e32 v86, v86, v87
	s_waitcnt lgkmcnt(5)
	v_pk_fma_f32 v[246:247], v[8:9], v[240:241], v[246:247]
	v_pk_fma_f32 v[248:249], v[10:11], v[242:243], v[248:249]
	s_waitcnt lgkmcnt(4)
	v_pk_mul_f32 v[82:83], v[48:49], v[250:251] op_sel:[0,1]
	v_add_f32_dpp v86, v86, v86 quad_perm:[1,0,3,2] row_mask:0xf bank_mask:0xf bound_ctrl:1
	v_pk_mul_f32 v[84:85], v[50:51], v[250:251] op_sel:[0,1]
	v_pk_fma_f32 v[4:5], v[4:5], v[40:41], v[82:83]
	v_add_f32_dpp v86, v86, v86 quad_perm:[2,3,0,1] row_mask:0xf bank_mask:0xf bound_ctrl:1
	v_pk_fma_f32 v[6:7], v[6:7], v[42:43], v[84:85]
	v_pk_mul_f32 v[82:83], v[52:53], v[250:251] op_sel:[0,1]
	v_add_f32_dpp v86, v86, v86 row_half_mirror row_mask:0xf bank_mask:0xf bound_ctrl:1
	v_pk_mul_f32 v[84:85], v[54:55], v[250:251] op_sel:[0,1]
	v_pk_fma_f32 v[8:9], v[8:9], v[44:45], v[82:83]
	v_pk_add_f32 v[246:247], v[246:247], v[248:249]
	v_pk_fma_f32 v[10:11], v[10:11], v[46:47], v[84:85]
	ds_read_b128 v[236:239], v38 offset:19200
	ds_read_b128 v[240:243], v38 offset:19216
	ds_read_b128 v[48:51], v38 offset:15360
	ds_read_b128 v[52:55], v38 offset:15376
	ds_read_b128 v[40:43], v38 offset:3072
	ds_read_b128 v[44:47], v38 offset:3088
	ds_read_b32 v250, v39 offset:1536
	v_add_f32_e32 v246, v246, v247
	s_waitcnt lgkmcnt(7)
; __device__ __forceinline__ void rwkv_scan_task(KP p, int l, bool samp, int b, int h, int hb, float* sm) {
;     ...
;         for (int s0 = 0; s0 < nst; s0 += 4) {
; #pragma unroll
;             for (int s4 = 0; s4 < 4; ++s4) {
;                 const int s = s0 + s4;
;                 const float* bs = bufp + s * 64 + ks * 8;
;                 f32x2 w2[4], kk2[4], ka2[4], kp2[4], r2[4];
; #pragma unroll
;                 for (int hh = 0; hh < 2; ++hh) {
;                     const float4 a = *(const float4*)(bs + hh * 4);
;                     const float4 bq = *(const float4*)(bs + 1024 + hh * 4);
;                     const float4 c = *(const float4*)(bs + 2048 + hh * 4);
;                     const float4 d = *(const float4*)(bs + 3072 + hh * 4);
;                     const float4 e = *(const float4*)(bs + 4096 + hh * 4);
;                     w2[2 * hh] = (f32x2){a.x, a.y}; w2[2 * hh + 1] = (f32x2){a.z, a.w};
;                     kk2[2 * hh] = (f32x2){bq.x, bq.y}; kk2[2 * hh + 1] = (f32x2){bq.z, bq.w};
;                     ka2[2 * hh] = (f32x2){c.x, c.y}; ka2[2 * hh + 1] = (f32x2){c.z, c.w};
;                     kp2[2 * hh] = (f32x2){d.x, d.y}; kp2[2 * hh + 1] = (f32x2){d.z, d.w};
;                     r2[2 * hh] = (f32x2){e.x, e.y}; r2[2 * hh + 1] = (f32x2){e.z, e.w};
;                 }
;                 const float vv = bufp[5120 + s * 32 + wid * 8 + rr];
;                 const f32x2 vv2 = (f32x2){vv, vv};
;                 f32x2 da = S[0] * kk2[0], db = S[1] * kk2[1];
;                 da = S[2] * kk2[2] + da; db = S[3] * kk2[3] + db;
;                 da = da + db;
;                 f32x2 u2[4];
; #pragma unroll
;                 for (int i = 0; i < 4; ++i) u2[i] = S[i] * w2[i] + vv2 * kp2[i];
;                 const float d1 = red8(da.x + da.y);
;                 const f32x2 nd = (f32x2){-d1, -d1};
; #pragma unroll
;                 for (int i = 0; i < 4; ++i) S[i] = nd * ka2[i] + u2[i];
;                 f32x2 ya = S[0] * r2[0], yb = S[1] * r2[1];
;                 ya = S[2] * r2[2] + ya; yb = S[3] * r2[3] + yb;
;                 ya = ya + yb;
;                 const float y = red8(ya.x + ya.y);
;                 yraw[(size_t)(row0 + tile * 16 + s) * 512 + h * 64 + vrow] = y;
;             }
	v_pk_fma_f32 v[4:5], v[56:57], v[86:87], v[4:5] op_sel_hi:[1,0,1] neg_lo:[0,1,0] neg_hi:[0,1,0]
	v_pk_fma_f32 v[6:7], v[58:59], v[86:87], v[6:7] op_sel_hi:[1,0,1] neg_lo:[0,1,0] neg_hi:[0,1,0]
	v_add_f32_dpp v246, v246, v246 quad_perm:[1,0,3,2] row_mask:0xf bank_mask:0xf bound_ctrl:1
	v_pk_fma_f32 v[8:9], v[60:61], v[86:87], v[8:9] op_sel_hi:[1,0,1] neg_lo:[0,1,0] neg_hi:[0,1,0]
	v_pk_fma_f32 v[10:11], v[62:63], v[86:87], v[10:11] op_sel_hi:[1,0,1] neg_lo:[0,1,0] neg_hi:[0,1,0]
	v_add_f32_dpp v246, v246, v246 quad_perm:[2,3,0,1] row_mask:0xf bank_mask:0xf bound_ctrl:1
	ds_read_b128 v[56:59], v38 offset:11264
	ds_read_b128 v[60:63], v38 offset:11280
	v_add_f32_dpp v246, v246, v246 row_half_mirror row_mask:0xf bank_mask:0xf bound_ctrl:1
	global_store_dword v[30:31], v246, off
	ds_read_b128 v[74:77], v38 offset:7424
	ds_read_b128 v[78:81], v38 offset:7440
	v_pk_mul_f32 v[86:87], v[4:5], v[66:67]
	v_pk_mul_f32 v[244:245], v[6:7], v[68:69]
	v_pk_fma_f32 v[86:87], v[8:9], v[70:71], v[86:87]
	v_pk_fma_f32 v[244:245], v[10:11], v[72:73], v[244:245]
	s_waitcnt lgkmcnt(10)
	v_pk_mul_f32 v[246:247], v[4:5], v[236:237]
	v_pk_add_f32 v[86:87], v[86:87], v[244:245]
	v_pk_mul_f32 v[248:249], v[6:7], v[238:239]
	v_add_f32_e32 v86, v86, v87
	s_waitcnt lgkmcnt(5)
	v_pk_fma_f32 v[246:247], v[8:9], v[240:241], v[246:247]
	v_pk_fma_f32 v[248:249], v[10:11], v[242:243], v[248:249]
	s_waitcnt lgkmcnt(4)
	v_pk_mul_f32 v[82:83], v[48:49], v[250:251] op_sel_hi:[1,0]
	v_add_f32_dpp v86, v86, v86 quad_perm:[1,0,3,2] row_mask:0xf bank_mask:0xf bound_ctrl:1
	v_pk_mul_f32 v[84:85], v[50:51], v[250:251] op_sel_hi:[1,0]
	v_pk_fma_f32 v[4:5], v[4:5], v[40:41], v[82:83]
	v_add_f32_dpp v86, v86, v86 quad_perm:[2,3,0,1] row_mask:0xf bank_mask:0xf bound_ctrl:1
	v_pk_fma_f32 v[6:7], v[6:7], v[42:43], v[84:85]
	v_pk_mul_f32 v[82:83], v[52:53], v[250:251] op_sel_hi:[1,0]
	v_add_f32_dpp v86, v86, v86 row_half_mirror row_mask:0xf bank_mask:0xf bound_ctrl:1
	v_pk_mul_f32 v[84:85], v[54:55], v[250:251] op_sel_hi:[1,0]
	v_pk_fma_f32 v[8:9], v[8:9], v[44:45], v[82:83]
	v_pk_add_f32 v[246:247], v[246:247], v[248:249]
	v_pk_fma_f32 v[10:11], v[10:11], v[46:47], v[84:85]
	ds_read_b128 v[236:239], v38 offset:19456
	ds_read_b128 v[240:243], v38 offset:19472
	ds_read_b128 v[48:51], v38 offset:15616
	ds_read_b128 v[52:55], v38 offset:15632
	ds_read_b128 v[40:43], v38 offset:3328
	ds_read_b128 v[44:47], v38 offset:3344
	ds_read_b32 v251, v39 offset:1664
	v_add_f32_e32 v246, v246, v247
	s_waitcnt lgkmcnt(7)
	v_pk_fma_f32 v[4:5], v[56:57], v[86:87], v[4:5] op_sel_hi:[1,0,1] neg_lo:[0,1,0] neg_hi:[0,1,0]
	v_pk_fma_f32 v[6:7], v[58:59], v[86:87], v[6:7] op_sel_hi:[1,0,1] neg_lo:[0,1,0] neg_hi:[0,1,0]
	v_add_f32_dpp v246, v246, v246 quad_perm:[1,0,3,2] row_mask:0xf bank_mask:0xf bound_ctrl:1
	v_pk_fma_f32 v[8:9], v[60:61], v[86:87], v[8:9] op_sel_hi:[1,0,1] neg_lo:[0,1,0] neg_hi:[0,1,0]
	v_pk_fma_f32 v[10:11], v[62:63], v[86:87], v[10:11] op_sel_hi:[1,0,1] neg_lo:[0,1,0] neg_hi:[0,1,0]
	v_add_f32_dpp v246, v246, v246 quad_perm:[2,3,0,1] row_mask:0xf bank_mask:0xf bound_ctrl:1
	ds_read_b128 v[56:59], v38 offset:11520
	ds_read_b128 v[60:63], v38 offset:11536
	v_add_f32_dpp v246, v246, v246 row_half_mirror row_mask:0xf bank_mask:0xf bound_ctrl:1
	global_store_dword v[30:31], v246, off offset:2048
	v_lshl_add_u64 v[30:31], v[30:31], 0, s[20:21]
	ds_read_b128 v[66:69], v38 offset:7680
	ds_read_b128 v[70:73], v38 offset:7696
	v_pk_mul_f32 v[86:87], v[4:5], v[74:75]
	v_pk_mul_f32 v[244:245], v[6:7], v[76:77]
	v_pk_fma_f32 v[86:87], v[8:9], v[78:79], v[86:87]
	v_pk_fma_f32 v[244:245], v[10:11], v[80:81], v[244:245]
	s_waitcnt lgkmcnt(9)
	v_pk_mul_f32 v[246:247], v[4:5], v[236:237]
	v_pk_add_f32 v[86:87], v[86:87], v[244:245]
	v_pk_mul_f32 v[248:249], v[6:7], v[238:239]
	v_add_f32_e32 v86, v86, v87
	v_pk_fma_f32 v[246:247], v[8:9], v[240:241], v[246:247]
	v_pk_fma_f32 v[248:249], v[10:11], v[242:243], v[248:249]
	s_waitcnt lgkmcnt(4)
	v_pk_mul_f32 v[82:83], v[48:49], v[250:251] op_sel:[0,1]
	v_add_f32_dpp v86, v86, v86 quad_perm:[1,0,3,2] row_mask:0xf bank_mask:0xf bound_ctrl:1
	v_pk_mul_f32 v[84:85], v[50:51], v[250:251] op_sel:[0,1]
	v_pk_fma_f32 v[4:5], v[4:5], v[40:41], v[82:83]
	v_add_f32_dpp v86, v86, v86 quad_perm:[2,3,0,1] row_mask:0xf bank_mask:0xf bound_ctrl:1
	v_pk_fma_f32 v[6:7], v[6:7], v[42:43], v[84:85]
	v_pk_mul_f32 v[82:83], v[52:53], v[250:251] op_sel:[0,1]
	v_add_f32_dpp v86, v86, v86 row_half_mirror row_mask:0xf bank_mask:0xf bound_ctrl:1
	v_pk_mul_f32 v[84:85], v[54:55], v[250:251] op_sel:[0,1]
	v_pk_fma_f32 v[8:9], v[8:9], v[44:45], v[82:83]
	v_pk_add_f32 v[246:247], v[246:247], v[248:249]
	v_pk_fma_f32 v[10:11], v[10:11], v[46:47], v[84:85]
	ds_read_b128 v[236:239], v38 offset:19712
	ds_read_b128 v[240:243], v38 offset:19728
	ds_read_b128 v[48:51], v38 offset:15872
	ds_read_b128 v[52:55], v38 offset:15888
	ds_read_b128 v[40:43], v38 offset:3584
	ds_read_b128 v[44:47], v38 offset:3600
	ds_read_b32 v250, v39 offset:1792
	v_add_f32_e32 v246, v246, v247
	s_waitcnt lgkmcnt(7)
	v_pk_fma_f32 v[4:5], v[56:57], v[86:87], v[4:5] op_sel_hi:[1,0,1] neg_lo:[0,1,0] neg_hi:[0,1,0]
	v_pk_fma_f32 v[6:7], v[58:59], v[86:87], v[6:7] op_sel_hi:[1,0,1] neg_lo:[0,1,0] neg_hi:[0,1,0]
	v_add_f32_dpp v246, v246, v246 quad_perm:[1,0,3,2] row_mask:0xf bank_mask:0xf bound_ctrl:1
	v_pk_fma_f32 v[8:9], v[60:61], v[86:87], v[8:9] op_sel_hi:[1,0,1] neg_lo:[0,1,0] neg_hi:[0,1,0]
	v_pk_fma_f32 v[10:11], v[62:63], v[86:87], v[10:11] op_sel_hi:[1,0,1] neg_lo:[0,1,0] neg_hi:[0,1,0]
	v_add_f32_dpp v246, v246, v246 quad_perm:[2,3,0,1] row_mask:0xf bank_mask:0xf bound_ctrl:1
	ds_read_b128 v[56:59], v38 offset:11776
	ds_read_b128 v[60:63], v38 offset:11792
	v_add_f32_dpp v246, v246, v246 row_half_mirror row_mask:0xf bank_mask:0xf bound_ctrl:1
	global_store_dword v[30:31], v246, off offset:-4096
	ds_read_b128 v[74:77], v38 offset:7936
	ds_read_b128 v[78:81], v38 offset:7952
	v_pk_mul_f32 v[86:87], v[4:5], v[66:67]
	v_pk_mul_f32 v[244:245], v[6:7], v[68:69]
	v_pk_fma_f32 v[86:87], v[8:9], v[70:71], v[86:87]
	v_pk_fma_f32 v[244:245], v[10:11], v[72:73], v[244:245]
	s_waitcnt lgkmcnt(10)
; __device__ __forceinline__ void rwkv_scan_task(KP p, int l, bool samp, int b, int h, int hb, float* sm) {
;     ...
;         for (int s0 = 0; s0 < nst; s0 += 4) {
; #pragma unroll
;             for (int s4 = 0; s4 < 4; ++s4) {
;                 const int s = s0 + s4;
;                 const float* bs = bufp + s * 64 + ks * 8;
;                 f32x2 w2[4], kk2[4], ka2[4], kp2[4], r2[4];
; #pragma unroll
;                 for (int hh = 0; hh < 2; ++hh) {
;                     const float4 a = *(const float4*)(bs + hh * 4);
;                     const float4 bq = *(const float4*)(bs + 1024 + hh * 4);
;                     const float4 c = *(const float4*)(bs + 2048 + hh * 4);
;                     const float4 d = *(const float4*)(bs + 3072 + hh * 4);
;                     const float4 e = *(const float4*)(bs + 4096 + hh * 4);
;                     w2[2 * hh] = (f32x2){a.x, a.y}; w2[2 * hh + 1] = (f32x2){a.z, a.w};
;                     kk2[2 * hh] = (f32x2){bq.x, bq.y}; kk2[2 * hh + 1] = (f32x2){bq.z, bq.w};
;                     ka2[2 * hh] = (f32x2){c.x, c.y}; ka2[2 * hh + 1] = (f32x2){c.z, c.w};
;                     kp2[2 * hh] = (f32x2){d.x, d.y}; kp2[2 * hh + 1] = (f32x2){d.z, d.w};
;                     r2[2 * hh] = (f32x2){e.x, e.y}; r2[2 * hh + 1] = (f32x2){e.z, e.w};
;                 }
;                 const float vv = bufp[5120 + s * 32 + wid * 8 + rr];
;                 const f32x2 vv2 = (f32x2){vv, vv};
;                 f32x2 da = S[0] * kk2[0], db = S[1] * kk2[1];
;                 da = S[2] * kk2[2] + da; db = S[3] * kk2[3] + db;
;                 da = da + db;
;                 f32x2 u2[4];
; #pragma unroll
;                 for (int i = 0; i < 4; ++i) u2[i] = S[i] * w2[i] + vv2 * kp2[i];
;                 const float d1 = red8(da.x + da.y);
;                 const f32x2 nd = (f32x2){-d1, -d1};
; #pragma unroll
;                 for (int i = 0; i < 4; ++i) S[i] = nd * ka2[i] + u2[i];
;                 f32x2 ya = S[0] * r2[0], yb = S[1] * r2[1];
;                 ya = S[2] * r2[2] + ya; yb = S[3] * r2[3] + yb;
;                 ya = ya + yb;
;                 const float y = red8(ya.x + ya.y);
;                 yraw[(size_t)(row0 + tile * 16 + s) * 512 + h * 64 + vrow] = y;
;             }
;         }
;     }
;     float* so = (samp ? p->out + O_SRWKV + ((size_t)((l * 128 + b) * 8 + h) * 64 + vrow) * 64
	v_pk_mul_f32 v[246:247], v[4:5], v[236:237]
	v_pk_add_f32 v[86:87], v[86:87], v[244:245]
	v_pk_mul_f32 v[248:249], v[6:7], v[238:239]
	v_add_f32_e32 v86, v86, v87
	s_waitcnt lgkmcnt(5)
	v_pk_fma_f32 v[246:247], v[8:9], v[240:241], v[246:247]
	v_pk_fma_f32 v[248:249], v[10:11], v[242:243], v[248:249]
	s_waitcnt lgkmcnt(4)
	v_pk_mul_f32 v[82:83], v[48:49], v[250:251] op_sel_hi:[1,0]
	v_add_f32_dpp v86, v86, v86 quad_perm:[1,0,3,2] row_mask:0xf bank_mask:0xf bound_ctrl:1
	v_pk_mul_f32 v[84:85], v[50:51], v[250:251] op_sel_hi:[1,0]
	v_pk_fma_f32 v[4:5], v[4:5], v[40:41], v[82:83]
	v_add_f32_dpp v86, v86, v86 quad_perm:[2,3,0,1] row_mask:0xf bank_mask:0xf bound_ctrl:1
	v_pk_fma_f32 v[6:7], v[6:7], v[42:43], v[84:85]
	v_pk_mul_f32 v[82:83], v[52:53], v[250:251] op_sel_hi:[1,0]
	v_add_f32_dpp v86, v86, v86 row_half_mirror row_mask:0xf bank_mask:0xf bound_ctrl:1
	v_pk_mul_f32 v[84:85], v[54:55], v[250:251] op_sel_hi:[1,0]
	v_pk_fma_f32 v[8:9], v[8:9], v[44:45], v[82:83]
	v_pk_add_f32 v[246:247], v[246:247], v[248:249]
	v_pk_fma_f32 v[10:11], v[10:11], v[46:47], v[84:85]
	ds_read_b128 v[236:239], v38 offset:19968
	ds_read_b128 v[240:243], v38 offset:19984
	ds_read_b128 v[48:51], v38 offset:16128
	ds_read_b128 v[52:55], v38 offset:16144
	ds_read_b128 v[40:43], v38 offset:3840
	ds_read_b128 v[44:47], v38 offset:3856
	ds_read_b32 v251, v39 offset:1920
	v_add_f32_e32 v246, v246, v247
	s_waitcnt lgkmcnt(7)
	v_pk_fma_f32 v[4:5], v[56:57], v[86:87], v[4:5] op_sel_hi:[1,0,1] neg_lo:[0,1,0] neg_hi:[0,1,0]
	v_pk_fma_f32 v[6:7], v[58:59], v[86:87], v[6:7] op_sel_hi:[1,0,1] neg_lo:[0,1,0] neg_hi:[0,1,0]
	v_add_f32_dpp v246, v246, v246 quad_perm:[1,0,3,2] row_mask:0xf bank_mask:0xf bound_ctrl:1
	v_pk_fma_f32 v[8:9], v[60:61], v[86:87], v[8:9] op_sel_hi:[1,0,1] neg_lo:[0,1,0] neg_hi:[0,1,0]
	v_pk_fma_f32 v[10:11], v[62:63], v[86:87], v[10:11] op_sel_hi:[1,0,1] neg_lo:[0,1,0] neg_hi:[0,1,0]
	v_add_f32_dpp v246, v246, v246 quad_perm:[2,3,0,1] row_mask:0xf bank_mask:0xf bound_ctrl:1
	ds_read_b128 v[56:59], v38 offset:12032
	ds_read_b128 v[60:63], v38 offset:12048
	v_add_f32_dpp v246, v246, v246 row_half_mirror row_mask:0xf bank_mask:0xf bound_ctrl:1
	global_store_dword v[30:31], v246, off offset:-2048
	v_pk_mul_f32 v[86:87], v[4:5], v[74:75]
	v_pk_mul_f32 v[244:245], v[6:7], v[76:77]
	v_pk_fma_f32 v[86:87], v[8:9], v[78:79], v[86:87]
	v_pk_fma_f32 v[244:245], v[10:11], v[80:81], v[244:245]
	s_waitcnt lgkmcnt(8)
	v_pk_mul_f32 v[246:247], v[4:5], v[236:237]
	v_pk_add_f32 v[86:87], v[86:87], v[244:245]
	v_pk_mul_f32 v[248:249], v[6:7], v[238:239]
	v_add_f32_e32 v86, v86, v87
	s_waitcnt lgkmcnt(5)
	v_pk_fma_f32 v[246:247], v[8:9], v[240:241], v[246:247]
	v_pk_fma_f32 v[248:249], v[10:11], v[242:243], v[248:249]
	s_waitcnt lgkmcnt(2)
	v_pk_mul_f32 v[82:83], v[48:49], v[250:251] op_sel:[0,1]
	v_add_f32_dpp v86, v86, v86 quad_perm:[1,0,3,2] row_mask:0xf bank_mask:0xf bound_ctrl:1
	v_pk_mul_f32 v[84:85], v[50:51], v[250:251] op_sel:[0,1]
	v_pk_fma_f32 v[4:5], v[4:5], v[40:41], v[82:83]
	v_add_f32_dpp v86, v86, v86 quad_perm:[2,3,0,1] row_mask:0xf bank_mask:0xf bound_ctrl:1
	v_pk_fma_f32 v[6:7], v[6:7], v[42:43], v[84:85]
	v_pk_mul_f32 v[82:83], v[52:53], v[250:251] op_sel:[0,1]
	v_add_f32_dpp v86, v86, v86 row_half_mirror row_mask:0xf bank_mask:0xf bound_ctrl:1
	v_pk_mul_f32 v[84:85], v[54:55], v[250:251] op_sel:[0,1]
	v_pk_fma_f32 v[8:9], v[8:9], v[44:45], v[82:83]
	v_pk_add_f32 v[246:247], v[246:247], v[248:249]
	v_pk_fma_f32 v[10:11], v[10:11], v[46:47], v[84:85]
	ds_read_b128 v[236:239], v38 offset:20224
	ds_read_b128 v[240:243], v38 offset:20240
	v_add_f32_e32 v246, v246, v247
	s_waitcnt lgkmcnt(2)
	v_pk_fma_f32 v[4:5], v[56:57], v[86:87], v[4:5] op_sel_hi:[1,0,1] neg_lo:[0,1,0] neg_hi:[0,1,0]
	v_pk_fma_f32 v[6:7], v[58:59], v[86:87], v[6:7] op_sel_hi:[1,0,1] neg_lo:[0,1,0] neg_hi:[0,1,0]
	v_add_f32_dpp v246, v246, v246 quad_perm:[1,0,3,2] row_mask:0xf bank_mask:0xf bound_ctrl:1
	v_pk_fma_f32 v[8:9], v[60:61], v[86:87], v[8:9] op_sel_hi:[1,0,1] neg_lo:[0,1,0] neg_hi:[0,1,0]
	v_pk_fma_f32 v[10:11], v[62:63], v[86:87], v[10:11] op_sel_hi:[1,0,1] neg_lo:[0,1,0] neg_hi:[0,1,0]
	v_add_f32_dpp v246, v246, v246 quad_perm:[2,3,0,1] row_mask:0xf bank_mask:0xf bound_ctrl:1
	s_nop 1
	v_add_f32_dpp v246, v246, v246 row_half_mirror row_mask:0xf bank_mask:0xf bound_ctrl:1
	global_store_dword v[30:31], v246, off
	s_waitcnt lgkmcnt(1)
	v_pk_mul_f32 v[246:247], v[4:5], v[236:237]
	v_pk_mul_f32 v[248:249], v[6:7], v[238:239]
	s_waitcnt lgkmcnt(0)
	v_pk_fma_f32 v[246:247], v[8:9], v[240:241], v[246:247]
	v_pk_fma_f32 v[248:249], v[10:11], v[242:243], v[248:249]
	s_nop 0
	v_pk_add_f32 v[246:247], v[246:247], v[248:249]
	s_nop 0
	v_add_f32_e32 v246, v246, v247
	s_nop 1
	v_add_f32_dpp v246, v246, v246 quad_perm:[1,0,3,2] row_mask:0xf bank_mask:0xf bound_ctrl:1
	s_nop 1
	v_add_f32_dpp v246, v246, v246 quad_perm:[2,3,0,1] row_mask:0xf bank_mask:0xf bound_ctrl:1
	s_nop 1
	v_add_f32_dpp v246, v246, v246 row_half_mirror row_mask:0xf bank_mask:0xf bound_ctrl:1
	global_store_dword v[30:31], v246, off offset:2048
	s_mov_b64 s[12:13], 0x8000
	s_cmpk_eq_i32 s11, 0x80
	v_lshl_add_u64 v[28:29], v[28:29], 0, s[12:13]
	s_cbranch_scc0 .LBB0_157
	v_readlane_b32 s12, v230, 25
	s_lshl_b32 s2, s12, 6
	v_readlane_b32 s11, v233, 22
	v_readlane_b32 s13, v230, 26
	s_add_i32 s12, s2, s11
	s_ashr_i32 s13, s12, 31
	s_waitcnt vmcnt(9)
	v_or_b32_e32 v0, v32, v33
	s_lshl_b64 s[12:13], s[12:13], 14
	v_ashrrev_i32_e32 v1, 31, v0
	s_add_u32 s12, s56, s12
	v_lshlrev_b64 v[0:1], 8, v[0:1]
	s_addc_u32 s13, s57, s13
	v_lshl_add_u64 v[0:1], s[12:13], 0, v[0:1]
	s_waitcnt vmcnt(4)
	v_mov_b32_e32 v23, v13
	v_lshl_add_u64 v[0:1], v[0:1], 0, v[22:23]
	s_mov_b64 s[12:13], 0x4400000
	v_lshl_add_u64 v[2:3], v[0:1], 0, s[12:13]
	v_add_co_u32_e32 v0, vcc, 0x4400000, v0
	s_nop 1
	v_addc_co_u32_e32 v1, vcc, 0, v1, vcc
	global_store_dwordx4 v[0:1], v[4:7], off nt
	global_store_dwordx4 v[2:3], v[8:11], off offset:16 nt
	s_barrier
